# per-phase s_setprio 1/0 flips deleted from the five GEMM K-loops (attention keeps its static raise for waves 4-7)
# speedup vs baseline: 1.0095x; 1.0073x over previous
; #define PG8_STAGE(bufoff, gbase, voff) do { _Pragma("unroll") for (int _i = 0; _i < 2; ++_i) \
;         __builtin_amdgcn_global_load_lds((const unsigned*)((const char*)(gbase) + (voff)[_i]), (PG8_LAS unsigned*)(lds + (bufoff) + ldsw + _i * 8192), 16, 0, 0); } while (0)
; #define PG8_LDA(dst, b, h) do { _Pragma("unroll") for (int m = 0; m < 4; ++m) _Pragma("unroll") for (int k = 0; k < 2; ++k) dst[m][k] = *(const PG8_LAS bf16x8*)(lds + PG8_SA(b, h) + aoff + m * 2048 + k * 1024); } while (0)
; #define PG8_LDB(dst, b, h) do { _Pragma("unroll") for (int n = 0; n < 2; ++n) _Pragma("unroll") for (int k = 0; k < 2; ++k) dst[n][k] = *(const PG8_LAS bf16x8*)(lds + PG8_SB(b, h) + boff + n * 2048 + k * 1024); } while (0)
; #define PG8_MMA(ai, bj, At, Bt) do { __builtin_amdgcn_s_setprio(1); _Pragma("unroll") for (int m = 0; m < 4; ++m) _Pragma("unroll") for (int n = 0; n < 2; ++n) _Pragma("unroll") for (int k = 0; k < 2; ++k) \
;         acc[ai][bj][m][n] = __builtin_amdgcn_mfma_f32_16x16x32_bf16(Bt[n][k], At[m][k], acc[ai][bj][m][n], 0, 0, 0); __builtin_amdgcn_s_setprio(0); } while (0)
; #define PG8_WAIT_V(n) asm volatile("s_waitcnt vmcnt(" #n ")" ::: "memory")
; #define PG8_WAIT_L(n) asm volatile("s_waitcnt lgkmcnt(" #n ")" ::: "memory")
; #define PG8_BAR __builtin_amdgcn_s_barrier()
; #define PG8_SCHED __builtin_amdgcn_sched_barrier(0)
; template <class Epi, class Sched, bool ALIGN_EPI = false, bool SP2 = false>
; __device__ __forceinline__ void gemm_phase(PG8_LAS unsigned char* lds, const Gemm g, const Sched& S, const Epi& E, const int wave_s) {
;     ...
;             PG8_LDB(B0, 0, 0); PG8_LDB(B1, 0, 1); PG8_SCHED; PG8_LDA(At, 0, 0); PG8_STAGE(PG8_SA(1, 1), a1 + hstep, voffA);
;             PG8_WAIT_V(8); PG8_WAIT_L(0); PG8_BAR; PG8_MMA(0, 0, At, B0); PG8_MMA(0, 1, At, B1); PG8_BAR; PG8_SCHED;
;             PG8_LDA(At, 0, 1); PG8_STAGE(PG8_SB(0, 0), b2, voffB); PG8_STAGE(PG8_SB(0, 1), b2 + hstep, voffB); PG8_STAGE(PG8_SA(0, 0), a2, voffA);
.LBB0_222:
	ds_read_b128 v[128:131], v217
	ds_read_b128 v[132:135], v217 offset:1024
	ds_read_b128 v[136:139], v217 offset:2048
	ds_read_b128 v[140:143], v217 offset:3072
	ds_read_b128 v[144:147], v218
	ds_read_b128 v[148:151], v218 offset:1024
	ds_read_b128 v[152:155], v218 offset:2048
	ds_read_b128 v[156:159], v218 offset:3072
	s_add_u32 s4, s2, 0xfffc0080
	s_addc_u32 s5, s3, -1
	s_cmp_eq_u32 s84, 12
	s_cselect_b32 s35, s25, s5
	s_cselect_b32 s34, s76, s4
	s_cselect_b32 s5, s17, s79
	s_cselect_b32 s4, s77, s78
	v_lshl_add_u64 v[206:207], s[2:3], 0, v[202:203]
	s_add_i32 m0, s31, 0xc000
	ds_read_b128 v[160:163], v219
	ds_read_b128 v[164:167], v219 offset:1024
	ds_read_b128 v[168:171], v219 offset:2048
	ds_read_b128 v[172:175], v219 offset:3072
	ds_read_b128 v[176:179], v219 offset:4096
	ds_read_b128 v[180:183], v219 offset:5120
	ds_read_b128 v[184:187], v219 offset:6144
	ds_read_b128 v[188:191], v219 offset:7168
	global_load_lds_dwordx4 v[206:207], off
	v_lshl_add_u64 v[206:207], s[2:3], 0, v[204:205]
	s_add_i32 m0, s31, 0xe000
	s_nop 0
	global_load_lds_dwordx4 v[206:207], off
	s_waitcnt vmcnt(8)
	s_waitcnt lgkmcnt(0)
	s_barrier
	s_waitcnt lgkmcnt(0)
	v_mfma_f32_16x16x32_bf16 v[124:127], v[128:131], v[160:163], v[124:127]
	v_mfma_f32_16x16x32_bf16 v[120:123], v[136:139], v[160:163], v[120:123]
	v_mfma_f32_16x16x32_bf16 v[108:111], v[128:131], v[168:171], v[108:111]
	v_mfma_f32_16x16x32_bf16 v[104:107], v[136:139], v[168:171], v[104:107]
	v_mfma_f32_16x16x32_bf16 v[92:95], v[128:131], v[176:179], v[92:95]
	v_mfma_f32_16x16x32_bf16 v[88:91], v[136:139], v[176:179], v[88:91]
	v_mfma_f32_16x16x32_bf16 v[76:79], v[128:131], v[184:187], v[76:79]
	v_mfma_f32_16x16x32_bf16 v[72:75], v[136:139], v[184:187], v[72:75]
	v_mfma_f32_16x16x32_bf16 v[124:127], v[132:135], v[164:167], v[124:127]
	v_mfma_f32_16x16x32_bf16 v[120:123], v[140:143], v[164:167], v[120:123]
	v_mfma_f32_16x16x32_bf16 v[108:111], v[132:135], v[172:175], v[108:111]
	v_mfma_f32_16x16x32_bf16 v[104:107], v[140:143], v[172:175], v[104:107]
	v_mfma_f32_16x16x32_bf16 v[92:95], v[132:135], v[180:183], v[92:95]
	v_mfma_f32_16x16x32_bf16 v[88:91], v[140:143], v[180:183], v[88:91]
	v_mfma_f32_16x16x32_bf16 v[76:79], v[132:135], v[188:191], v[76:79]
	v_mfma_f32_16x16x32_bf16 v[72:75], v[140:143], v[188:191], v[72:75]
	v_mfma_f32_16x16x32_bf16 v[116:119], v[144:147], v[160:163], v[116:119]
	v_mfma_f32_16x16x32_bf16 v[112:115], v[152:155], v[160:163], v[112:115]
	v_mfma_f32_16x16x32_bf16 v[100:103], v[144:147], v[168:171], v[100:103]
	v_mfma_f32_16x16x32_bf16 v[96:99], v[152:155], v[168:171], v[96:99]
	v_mfma_f32_16x16x32_bf16 v[84:87], v[144:147], v[176:179], v[84:87]
	v_mfma_f32_16x16x32_bf16 v[80:83], v[152:155], v[176:179], v[80:83]
	v_mfma_f32_16x16x32_bf16 v[68:71], v[144:147], v[184:187], v[68:71]
	v_mfma_f32_16x16x32_bf16 v[64:67], v[152:155], v[184:187], v[64:67]
	v_mfma_f32_16x16x32_bf16 v[116:119], v[148:151], v[164:167], v[116:119]
	v_mfma_f32_16x16x32_bf16 v[112:115], v[156:159], v[164:167], v[112:115]
	v_mfma_f32_16x16x32_bf16 v[100:103], v[148:151], v[172:175], v[100:103]
	v_mfma_f32_16x16x32_bf16 v[96:99], v[156:159], v[172:175], v[96:99]
	v_mfma_f32_16x16x32_bf16 v[84:87], v[148:151], v[180:183], v[84:87]
	v_mfma_f32_16x16x32_bf16 v[80:83], v[156:159], v[180:183], v[80:83]
	v_mfma_f32_16x16x32_bf16 v[68:71], v[148:151], v[188:191], v[68:71]
	v_mfma_f32_16x16x32_bf16 v[64:67], v[156:159], v[188:191], v[64:67]
	s_barrier
	s_add_i32 s85, s71, s40
	v_lshl_add_u64 v[206:207], s[4:5], 0, v[196:197]
	s_mov_b32 m0, s85
	ds_read_b128 v[160:163], v219 offset:16384
	ds_read_b128 v[164:167], v219 offset:17408
	ds_read_b128 v[168:171], v219 offset:18432
	ds_read_b128 v[172:175], v219 offset:19456
	ds_read_b128 v[176:179], v219 offset:20480
	ds_read_b128 v[180:183], v219 offset:21504
	ds_read_b128 v[184:187], v219 offset:22528
	ds_read_b128 v[188:191], v219 offset:23552
	global_load_lds_dwordx4 v[206:207], off
	s_add_i32 m0, s85, 0x2000
	s_add_u32 s86, s4, 0x40000
	v_lshl_add_u64 v[208:209], s[4:5], 0, v[192:193]
	s_addc_u32 s87, s5, 0
	s_add_i32 s85, s72, s40
	global_load_lds_dwordx4 v[208:209], off
	v_lshl_add_u64 v[210:211], s[86:87], 0, v[196:197]
	s_mov_b32 m0, s85
	v_lshl_add_u64 v[212:213], s[34:35], 0, v[194:195]
	global_load_lds_dwordx4 v[210:211], off
	v_lshl_add_u64 v[210:211], s[86:87], 0, v[192:193]
	s_add_i32 m0, s85, 0x2000
	s_nop 0
	global_load_lds_dwordx4 v[210:211], off
	v_lshl_add_u64 v[210:211], s[34:35], 0, v[198:199]
	s_mov_b32 m0, s31
	s_nop 0
	global_load_lds_dwordx4 v[210:211], off
	s_mov_b32 m0, s43
	s_nop 0
	global_load_lds_dwordx4 v[212:213], off
	s_waitcnt vmcnt(8)
	s_waitcnt lgkmcnt(0)
	s_barrier
; #define PG8_STAGE(bufoff, gbase, voff) do { _Pragma("unroll") for (int _i = 0; _i < 2; ++_i) \
;         __builtin_amdgcn_global_load_lds((const unsigned*)((const char*)(gbase) + (voff)[_i]), (PG8_LAS unsigned*)(lds + (bufoff) + ldsw + _i * 8192), 16, 0, 0); } while (0)
; #define PG8_LDA(dst, b, h) do { _Pragma("unroll") for (int m = 0; m < 4; ++m) _Pragma("unroll") for (int k = 0; k < 2; ++k) dst[m][k] = *(const PG8_LAS bf16x8*)(lds + PG8_SA(b, h) + aoff + m * 2048 + k * 1024); } while (0)
; #define PG8_LDB(dst, b, h) do { _Pragma("unroll") for (int n = 0; n < 2; ++n) _Pragma("unroll") for (int k = 0; k < 2; ++k) dst[n][k] = *(const PG8_LAS bf16x8*)(lds + PG8_SB(b, h) + boff + n * 2048 + k * 1024); } while (0)
; #define PG8_MMA(ai, bj, At, Bt) do { __builtin_amdgcn_s_setprio(1); _Pragma("unroll") for (int m = 0; m < 4; ++m) _Pragma("unroll") for (int n = 0; n < 2; ++n) _Pragma("unroll") for (int k = 0; k < 2; ++k) \
;         acc[ai][bj][m][n] = __builtin_amdgcn_mfma_f32_16x16x32_bf16(Bt[n][k], At[m][k], acc[ai][bj][m][n], 0, 0, 0); __builtin_amdgcn_s_setprio(0); } while (0)
; #define PG8_WAIT_V(n) asm volatile("s_waitcnt vmcnt(" #n ")" ::: "memory")
; #define PG8_WAIT_L(n) asm volatile("s_waitcnt lgkmcnt(" #n ")" ::: "memory")
; #define PG8_BAR __builtin_amdgcn_s_barrier()
; #define PG8_SCHED __builtin_amdgcn_sched_barrier(0)
; template <class Epi, class Sched, bool ALIGN_EPI = false, bool SP2 = false>
; __device__ __forceinline__ void gemm_phase(PG8_LAS unsigned char* lds, const Gemm g, const Sched& S, const Epi& E, const int wave_s) {
;     ...
;             PG8_WAIT_V(8); PG8_WAIT_L(0); PG8_BAR; PG8_MMA(1, 0, At, B0); PG8_MMA(1, 1, At, B1); PG8_BAR; PG8_SCHED;
;             PG8_LDB(B0, 1, 0); PG8_LDB(B1, 1, 1); PG8_SCHED; PG8_LDA(At, 1, 0); PG8_STAGE(PG8_SA(0, 1), a2 + hstep, voffA);
;             PG8_WAIT_V(8); PG8_WAIT_L(0); PG8_BAR; PG8_MMA(0, 0, At, B0); PG8_MMA(0, 1, At, B1); PG8_BAR; PG8_SCHED;
	s_waitcnt lgkmcnt(0)
	v_mfma_f32_16x16x32_bf16 v[60:63], v[128:131], v[160:163], v[60:63]
	v_mfma_f32_16x16x32_bf16 v[56:59], v[136:139], v[160:163], v[56:59]
	v_mfma_f32_16x16x32_bf16 v[44:47], v[128:131], v[168:171], v[44:47]
	v_mfma_f32_16x16x32_bf16 v[40:43], v[136:139], v[168:171], v[40:43]
	v_mfma_f32_16x16x32_bf16 v[28:31], v[128:131], v[176:179], v[28:31]
	v_mfma_f32_16x16x32_bf16 v[24:27], v[136:139], v[176:179], v[24:27]
	v_mfma_f32_16x16x32_bf16 v[12:15], v[128:131], v[184:187], v[12:15]
	v_mfma_f32_16x16x32_bf16 v[8:11], v[136:139], v[184:187], v[8:11]
	v_mfma_f32_16x16x32_bf16 v[60:63], v[132:135], v[164:167], v[60:63]
	v_mfma_f32_16x16x32_bf16 v[56:59], v[140:143], v[164:167], v[56:59]
	v_mfma_f32_16x16x32_bf16 v[44:47], v[132:135], v[172:175], v[44:47]
	v_mfma_f32_16x16x32_bf16 v[40:43], v[140:143], v[172:175], v[40:43]
	v_mfma_f32_16x16x32_bf16 v[28:31], v[132:135], v[180:183], v[28:31]
	v_mfma_f32_16x16x32_bf16 v[24:27], v[140:143], v[180:183], v[24:27]
	v_mfma_f32_16x16x32_bf16 v[12:15], v[132:135], v[188:191], v[12:15]
	v_mfma_f32_16x16x32_bf16 v[8:11], v[140:143], v[188:191], v[8:11]
	v_mfma_f32_16x16x32_bf16 v[52:55], v[144:147], v[160:163], v[52:55]
	v_mfma_f32_16x16x32_bf16 v[48:51], v[152:155], v[160:163], v[48:51]
	v_mfma_f32_16x16x32_bf16 v[36:39], v[144:147], v[168:171], v[36:39]
	v_mfma_f32_16x16x32_bf16 v[32:35], v[152:155], v[168:171], v[32:35]
	v_mfma_f32_16x16x32_bf16 v[20:23], v[144:147], v[176:179], v[20:23]
	v_mfma_f32_16x16x32_bf16 v[16:19], v[152:155], v[176:179], v[16:19]
	v_mfma_f32_16x16x32_bf16 v[4:7], v[144:147], v[184:187], v[4:7]
	v_mfma_f32_16x16x32_bf16 v[0:3], v[152:155], v[184:187], v[0:3]
	v_mfma_f32_16x16x32_bf16 v[52:55], v[148:151], v[164:167], v[52:55]
	v_mfma_f32_16x16x32_bf16 v[48:51], v[156:159], v[164:167], v[48:51]
	v_mfma_f32_16x16x32_bf16 v[36:39], v[148:151], v[172:175], v[36:39]
	v_mfma_f32_16x16x32_bf16 v[32:35], v[156:159], v[172:175], v[32:35]
	v_mfma_f32_16x16x32_bf16 v[20:23], v[148:151], v[180:183], v[20:23]
	v_mfma_f32_16x16x32_bf16 v[16:19], v[156:159], v[180:183], v[16:19]
	v_mfma_f32_16x16x32_bf16 v[4:7], v[148:151], v[188:191], v[4:7]
	v_mfma_f32_16x16x32_bf16 v[0:3], v[156:159], v[188:191], v[0:3]
	s_barrier
	s_add_i32 s85, 0, 0x18000
	s_add_i32 s86, 0, 0x1c000
	v_add_u32_e32 v140, s85, v216
	v_add_u32_e32 v156, s86, v216
	ds_read_b128 v[128:131], v140
	ds_read_b128 v[132:135], v140 offset:1024
	ds_read_b128 v[136:139], v140 offset:2048
	ds_read_b128 v[140:143], v140 offset:3072
	ds_read_b128 v[144:147], v156
	ds_read_b128 v[148:151], v156 offset:1024
	ds_read_b128 v[152:155], v156 offset:2048
	ds_read_b128 v[156:159], v156 offset:3072
	s_add_u32 s34, s34, 0x40000
	s_addc_u32 s35, s35, 0
	s_mov_b32 m0, s52
	v_lshl_add_u64 v[226:227], s[34:35], 0, v[198:199]
	ds_read_b128 v[160:163], v219 offset:32768
	ds_read_b128 v[164:167], v219 offset:33792
	ds_read_b128 v[168:171], v219 offset:34816
	ds_read_b128 v[172:175], v219 offset:35840
	ds_read_b128 v[176:179], v219 offset:36864
	ds_read_b128 v[180:183], v219 offset:37888
	ds_read_b128 v[184:187], v219 offset:38912
	ds_read_b128 v[188:191], v219 offset:39936
	global_load_lds_dwordx4 v[226:227], off
	v_lshl_add_u64 v[226:227], s[34:35], 0, v[194:195]
	s_mov_b32 m0, s53
	s_nop 0
	global_load_lds_dwordx4 v[226:227], off
	s_waitcnt vmcnt(8)
	s_waitcnt lgkmcnt(0)
	s_barrier
	s_waitcnt lgkmcnt(0)
	v_mfma_f32_16x16x32_bf16 v[124:127], v[128:131], v[160:163], v[124:127]
	v_mfma_f32_16x16x32_bf16 v[120:123], v[136:139], v[160:163], v[120:123]
	v_mfma_f32_16x16x32_bf16 v[108:111], v[128:131], v[168:171], v[108:111]
	v_mfma_f32_16x16x32_bf16 v[104:107], v[136:139], v[168:171], v[104:107]
	v_mfma_f32_16x16x32_bf16 v[92:95], v[128:131], v[176:179], v[92:95]
	v_mfma_f32_16x16x32_bf16 v[88:91], v[136:139], v[176:179], v[88:91]
	v_mfma_f32_16x16x32_bf16 v[76:79], v[128:131], v[184:187], v[76:79]
	v_mfma_f32_16x16x32_bf16 v[72:75], v[136:139], v[184:187], v[72:75]
	v_mfma_f32_16x16x32_bf16 v[124:127], v[132:135], v[164:167], v[124:127]
	v_mfma_f32_16x16x32_bf16 v[120:123], v[140:143], v[164:167], v[120:123]
	v_mfma_f32_16x16x32_bf16 v[108:111], v[132:135], v[172:175], v[108:111]
	v_mfma_f32_16x16x32_bf16 v[104:107], v[140:143], v[172:175], v[104:107]
	v_mfma_f32_16x16x32_bf16 v[92:95], v[132:135], v[180:183], v[92:95]
	v_mfma_f32_16x16x32_bf16 v[88:91], v[140:143], v[180:183], v[88:91]
	v_mfma_f32_16x16x32_bf16 v[76:79], v[132:135], v[188:191], v[76:79]
	v_mfma_f32_16x16x32_bf16 v[72:75], v[140:143], v[188:191], v[72:75]
	v_mfma_f32_16x16x32_bf16 v[116:119], v[144:147], v[160:163], v[116:119]
	v_mfma_f32_16x16x32_bf16 v[112:115], v[152:155], v[160:163], v[112:115]
	v_mfma_f32_16x16x32_bf16 v[100:103], v[144:147], v[168:171], v[100:103]
	v_mfma_f32_16x16x32_bf16 v[96:99], v[152:155], v[168:171], v[96:99]
	v_mfma_f32_16x16x32_bf16 v[84:87], v[144:147], v[176:179], v[84:87]
	v_mfma_f32_16x16x32_bf16 v[80:83], v[152:155], v[176:179], v[80:83]
	v_mfma_f32_16x16x32_bf16 v[68:71], v[144:147], v[184:187], v[68:71]
	v_mfma_f32_16x16x32_bf16 v[64:67], v[152:155], v[184:187], v[64:67]
	v_mfma_f32_16x16x32_bf16 v[116:119], v[148:151], v[164:167], v[116:119]
	v_mfma_f32_16x16x32_bf16 v[112:115], v[156:159], v[164:167], v[112:115]
	v_mfma_f32_16x16x32_bf16 v[100:103], v[148:151], v[172:175], v[100:103]
	v_mfma_f32_16x16x32_bf16 v[96:99], v[156:159], v[172:175], v[96:99]
	v_mfma_f32_16x16x32_bf16 v[84:87], v[148:151], v[180:183], v[84:87]
	v_mfma_f32_16x16x32_bf16 v[80:83], v[156:159], v[180:183], v[80:83]
	v_mfma_f32_16x16x32_bf16 v[68:71], v[148:151], v[188:191], v[68:71]
	v_mfma_f32_16x16x32_bf16 v[64:67], v[156:159], v[188:191], v[64:67]
	s_barrier
; #define PG8_STAGE(bufoff, gbase, voff) do { _Pragma("unroll") for (int _i = 0; _i < 2; ++_i) \
;         __builtin_amdgcn_global_load_lds((const unsigned*)((const char*)(gbase) + (voff)[_i]), (PG8_LAS unsigned*)(lds + (bufoff) + ldsw + _i * 8192), 16, 0, 0); } while (0)
; #define PG8_LDA(dst, b, h) do { _Pragma("unroll") for (int m = 0; m < 4; ++m) _Pragma("unroll") for (int k = 0; k < 2; ++k) dst[m][k] = *(const PG8_LAS bf16x8*)(lds + PG8_SA(b, h) + aoff + m * 2048 + k * 1024); } while (0)
; #define PG8_MMA(ai, bj, At, Bt) do { __builtin_amdgcn_s_setprio(1); _Pragma("unroll") for (int m = 0; m < 4; ++m) _Pragma("unroll") for (int n = 0; n < 2; ++n) _Pragma("unroll") for (int k = 0; k < 2; ++k) \
;         acc[ai][bj][m][n] = __builtin_amdgcn_mfma_f32_16x16x32_bf16(Bt[n][k], At[m][k], acc[ai][bj][m][n], 0, 0, 0); __builtin_amdgcn_s_setprio(0); } while (0)
; #define PG8_WAIT_V(n) asm volatile("s_waitcnt vmcnt(" #n ")" ::: "memory")
; #define PG8_WAIT_L(n) asm volatile("s_waitcnt lgkmcnt(" #n ")" ::: "memory")
; #define PG8_BAR __builtin_amdgcn_s_barrier()
; #define PG8_SCHED __builtin_amdgcn_sched_barrier(0)
; template <class Epi, class Sched, bool ALIGN_EPI = false, bool SP2 = false>
; __device__ __forceinline__ void gemm_phase(PG8_LAS unsigned char* lds, const Gemm g, const Sched& S, const Epi& E, const int wave_s) {
;     ...
;             PG8_LDA(At, 1, 1); PG8_STAGE(PG8_SB(1, 0), b3, voffB); PG8_STAGE(PG8_SB(1, 1), b3 + hstep, voffB); PG8_STAGE(PG8_SA(1, 0), a3, voffA);
;             PG8_WAIT_V(8); PG8_WAIT_L(0); PG8_BAR; PG8_MMA(1, 0, At, B0); PG8_MMA(1, 1, At, B1); PG8_BAR; PG8_SCHED;
	s_add_i32 s34, s85, s40
	v_lshl_add_u64 v[206:207], v[206:207], 0, s[12:13]
	s_mov_b32 m0, s34
	ds_read_b128 v[160:163], v219 offset:49152
	ds_read_b128 v[164:167], v219 offset:50176
	ds_read_b128 v[168:171], v219 offset:51200
	ds_read_b128 v[172:175], v219 offset:52224
	ds_read_b128 v[176:179], v219 offset:53248
	ds_read_b128 v[180:183], v219 offset:54272
	ds_read_b128 v[184:187], v219 offset:55296
	ds_read_b128 v[188:191], v219 offset:56320
	global_load_lds_dwordx4 v[206:207], off
	s_add_i32 m0, s34, 0x2000
	s_add_u32 s4, s4, 0x40080
	v_lshl_add_u64 v[206:207], v[208:209], 0, s[12:13]
	s_addc_u32 s5, s5, 0
	s_add_i32 s34, s86, s40
	global_load_lds_dwordx4 v[206:207], off
	v_lshl_add_u64 v[206:207], s[4:5], 0, v[196:197]
	s_mov_b32 m0, s34
	s_nop 0
	global_load_lds_dwordx4 v[206:207], off
	v_lshl_add_u64 v[206:207], s[4:5], 0, v[192:193]
	s_add_i32 m0, s34, 0x2000
	s_nop 0
	global_load_lds_dwordx4 v[206:207], off
	v_lshl_add_u64 v[206:207], v[210:211], 0, s[12:13]
	s_mov_b32 m0, s65
	s_nop 0
	global_load_lds_dwordx4 v[206:207], off
	v_lshl_add_u64 v[206:207], v[212:213], 0, s[12:13]
	s_mov_b32 m0, s66
	s_nop 0
	global_load_lds_dwordx4 v[206:207], off
	s_waitcnt vmcnt(8)
	s_waitcnt lgkmcnt(0)
	s_barrier
	s_waitcnt lgkmcnt(0)
	v_mfma_f32_16x16x32_bf16 v[60:63], v[128:131], v[160:163], v[60:63]
	v_mfma_f32_16x16x32_bf16 v[56:59], v[136:139], v[160:163], v[56:59]
	v_mfma_f32_16x16x32_bf16 v[44:47], v[128:131], v[168:171], v[44:47]
	v_mfma_f32_16x16x32_bf16 v[40:43], v[136:139], v[168:171], v[40:43]
	v_mfma_f32_16x16x32_bf16 v[28:31], v[128:131], v[176:179], v[28:31]
	v_mfma_f32_16x16x32_bf16 v[24:27], v[136:139], v[176:179], v[24:27]
	v_mfma_f32_16x16x32_bf16 v[12:15], v[128:131], v[184:187], v[12:15]
	v_mfma_f32_16x16x32_bf16 v[8:11], v[136:139], v[184:187], v[8:11]
	v_mfma_f32_16x16x32_bf16 v[60:63], v[132:135], v[164:167], v[60:63]
	v_mfma_f32_16x16x32_bf16 v[56:59], v[140:143], v[164:167], v[56:59]
	v_mfma_f32_16x16x32_bf16 v[44:47], v[132:135], v[172:175], v[44:47]
	v_mfma_f32_16x16x32_bf16 v[40:43], v[140:143], v[172:175], v[40:43]
	v_mfma_f32_16x16x32_bf16 v[28:31], v[132:135], v[180:183], v[28:31]
	v_mfma_f32_16x16x32_bf16 v[24:27], v[140:143], v[180:183], v[24:27]
	v_mfma_f32_16x16x32_bf16 v[12:15], v[132:135], v[188:191], v[12:15]
	v_mfma_f32_16x16x32_bf16 v[8:11], v[140:143], v[188:191], v[8:11]
	v_mfma_f32_16x16x32_bf16 v[52:55], v[144:147], v[160:163], v[52:55]
	v_mfma_f32_16x16x32_bf16 v[48:51], v[152:155], v[160:163], v[48:51]
	v_mfma_f32_16x16x32_bf16 v[36:39], v[144:147], v[168:171], v[36:39]
	v_mfma_f32_16x16x32_bf16 v[32:35], v[152:155], v[168:171], v[32:35]
	v_mfma_f32_16x16x32_bf16 v[20:23], v[144:147], v[176:179], v[20:23]
	v_mfma_f32_16x16x32_bf16 v[16:19], v[152:155], v[176:179], v[16:19]
	v_mfma_f32_16x16x32_bf16 v[4:7], v[144:147], v[184:187], v[4:7]
	v_mfma_f32_16x16x32_bf16 v[0:3], v[152:155], v[184:187], v[0:3]
	v_mfma_f32_16x16x32_bf16 v[52:55], v[148:151], v[164:167], v[52:55]
	v_mfma_f32_16x16x32_bf16 v[48:51], v[156:159], v[164:167], v[48:51]
	v_mfma_f32_16x16x32_bf16 v[36:39], v[148:151], v[172:175], v[36:39]
	v_mfma_f32_16x16x32_bf16 v[32:35], v[156:159], v[172:175], v[32:35]
	v_mfma_f32_16x16x32_bf16 v[20:23], v[148:151], v[180:183], v[20:23]
	v_mfma_f32_16x16x32_bf16 v[16:19], v[156:159], v[180:183], v[16:19]
	v_mfma_f32_16x16x32_bf16 v[4:7], v[148:151], v[188:191], v[4:7]
	v_mfma_f32_16x16x32_bf16 v[0:3], v[156:159], v[188:191], v[0:3]
	s_barrier
	s_add_i32 s84, s84, 2
	s_add_u32 s2, s2, 0x100
	s_addc_u32 s3, s3, 0
	s_add_u32 s78, s78, 0x100
	s_addc_u32 s79, s79, 0
	s_cmp_gt_u32 s84, 13
	s_cbranch_scc0 .LBB0_222
	s_and_b64 vcc, exec, s[14:15]
	s_cbranch_vccz .LBB0_225
	s_barrier

; #define PG8_STAGE(bufoff, gbase, voff) do { _Pragma("unroll") for (int _i = 0; _i < 2; ++_i) \
;         __builtin_amdgcn_global_load_lds((const unsigned*)((const char*)(gbase) + (voff)[_i]), (PG8_LAS unsigned*)(lds + (bufoff) + ldsw + _i * 8192), 16, 0, 0); } while (0)
; #define PG8_LDA(dst, b, h) do { _Pragma("unroll") for (int m = 0; m < 4; ++m) _Pragma("unroll") for (int k = 0; k < 2; ++k) dst[m][k] = *(const PG8_LAS bf16x8*)(lds + PG8_SA(b, h) + aoff + m * 2048 + k * 1024); } while (0)
; #define PG8_LDB(dst, b, h) do { _Pragma("unroll") for (int n = 0; n < 2; ++n) _Pragma("unroll") for (int k = 0; k < 2; ++k) dst[n][k] = *(const PG8_LAS bf16x8*)(lds + PG8_SB(b, h) + boff + n * 2048 + k * 1024); } while (0)
; #define PG8_MMA(ai, bj, At, Bt) do { __builtin_amdgcn_s_setprio(1); _Pragma("unroll") for (int m = 0; m < 4; ++m) _Pragma("unroll") for (int n = 0; n < 2; ++n) _Pragma("unroll") for (int k = 0; k < 2; ++k) \
;         acc[ai][bj][m][n] = __builtin_amdgcn_mfma_f32_16x16x32_bf16(Bt[n][k], At[m][k], acc[ai][bj][m][n], 0, 0, 0); __builtin_amdgcn_s_setprio(0); } while (0)
; #define PG8_WAIT_V(n) asm volatile("s_waitcnt vmcnt(" #n ")" ::: "memory")
; #define PG8_WAIT_L(n) asm volatile("s_waitcnt lgkmcnt(" #n ")" ::: "memory")
; #define PG8_BAR __builtin_amdgcn_s_barrier()
; #define PG8_SCHED __builtin_amdgcn_sched_barrier(0)
; template <class Epi, class Sched, bool ALIGN_EPI = false, bool SP2 = false>
; __device__ __forceinline__ void gemm_phase(PG8_LAS unsigned char* lds, const Gemm g, const Sched& S, const Epi& E, const int wave_s) {
;     ...
;             PG8_LDB(B0, 0, 0); PG8_LDB(B1, 0, 1); PG8_SCHED; PG8_LDA(At, 0, 0); PG8_STAGE(PG8_SA(1, 1), a1 + hstep, voffA);
;             PG8_WAIT_V(8); PG8_WAIT_L(0); PG8_BAR; PG8_MMA(0, 0, At, B0); PG8_MMA(0, 1, At, B1); PG8_BAR; PG8_SCHED;
;             PG8_LDA(At, 0, 1); PG8_STAGE(PG8_SB(0, 0), b2, voffB); PG8_STAGE(PG8_SB(0, 1), b2 + hstep, voffB); PG8_STAGE(PG8_SA(0, 0), a2, voffA);
.LBB0_250:
	ds_read_b128 v[146:149], v153
	ds_read_b128 v[156:159], v153 offset:1024
	ds_read_b128 v[160:163], v153 offset:2048
	ds_read_b128 v[164:167], v153 offset:3072
	ds_read_b128 v[168:171], v154
	ds_read_b128 v[172:175], v154 offset:1024
	ds_read_b128 v[176:179], v154 offset:2048
	ds_read_b128 v[180:183], v154 offset:3072
	s_add_u32 s30, s28, 0xfffc0080
	s_addc_u32 s31, s29, -1
	s_cmp_eq_u32 s75, 12
	s_cselect_b32 s35, s13, s31
	s_cselect_b32 s34, s25, s30
	s_cselect_b32 s31, s3, s74
	s_cselect_b32 s30, s27, s73
	v_lshl_add_u64 v[216:217], s[28:29], 0, v[138:139]
	s_add_i32 m0, s52, 0xc000
	ds_read_b128 v[184:187], v155
	ds_read_b128 v[188:191], v155 offset:1024
	ds_read_b128 v[192:195], v155 offset:2048
	ds_read_b128 v[196:199], v155 offset:3072
	ds_read_b128 v[200:203], v155 offset:4096
	ds_read_b128 v[204:207], v155 offset:5120
	ds_read_b128 v[208:211], v155 offset:6144
	ds_read_b128 v[212:215], v155 offset:7168
	global_load_lds_dwordx4 v[216:217], off
	v_lshl_add_u64 v[216:217], s[28:29], 0, v[140:141]
	s_add_i32 m0, s52, 0xe000
	s_nop 0
	global_load_lds_dwordx4 v[216:217], off
	s_waitcnt vmcnt(8)
	s_waitcnt lgkmcnt(0)
	s_barrier
	s_waitcnt lgkmcnt(0)
	v_mfma_f32_16x16x32_bf16 v[124:127], v[146:149], v[184:187], v[124:127]
	v_mfma_f32_16x16x32_bf16 v[120:123], v[160:163], v[184:187], v[120:123]
	v_mfma_f32_16x16x32_bf16 v[112:115], v[146:149], v[192:195], v[112:115]
	v_mfma_f32_16x16x32_bf16 v[104:107], v[160:163], v[192:195], v[104:107]
	v_mfma_f32_16x16x32_bf16 v[96:99], v[146:149], v[200:203], v[96:99]
	v_mfma_f32_16x16x32_bf16 v[88:91], v[160:163], v[200:203], v[88:91]
	v_mfma_f32_16x16x32_bf16 v[80:83], v[146:149], v[208:211], v[80:83]
	v_mfma_f32_16x16x32_bf16 v[72:75], v[160:163], v[208:211], v[72:75]
	v_mfma_f32_16x16x32_bf16 v[124:127], v[156:159], v[188:191], v[124:127]
	v_mfma_f32_16x16x32_bf16 v[120:123], v[164:167], v[188:191], v[120:123]
	v_mfma_f32_16x16x32_bf16 v[112:115], v[156:159], v[196:199], v[112:115]
	v_mfma_f32_16x16x32_bf16 v[104:107], v[164:167], v[196:199], v[104:107]
	v_mfma_f32_16x16x32_bf16 v[96:99], v[156:159], v[204:207], v[96:99]
	v_mfma_f32_16x16x32_bf16 v[88:91], v[164:167], v[204:207], v[88:91]
	v_mfma_f32_16x16x32_bf16 v[80:83], v[156:159], v[212:215], v[80:83]
	v_mfma_f32_16x16x32_bf16 v[72:75], v[164:167], v[212:215], v[72:75]
	v_mfma_f32_16x16x32_bf16 v[116:119], v[168:171], v[184:187], v[116:119]
	v_mfma_f32_16x16x32_bf16 v[108:111], v[176:179], v[184:187], v[108:111]
	v_mfma_f32_16x16x32_bf16 v[100:103], v[168:171], v[192:195], v[100:103]
	v_mfma_f32_16x16x32_bf16 v[92:95], v[176:179], v[192:195], v[92:95]
	v_mfma_f32_16x16x32_bf16 v[84:87], v[168:171], v[200:203], v[84:87]
	v_mfma_f32_16x16x32_bf16 v[76:79], v[176:179], v[200:203], v[76:79]
	v_mfma_f32_16x16x32_bf16 v[68:71], v[168:171], v[208:211], v[68:71]
	v_mfma_f32_16x16x32_bf16 v[64:67], v[176:179], v[208:211], v[64:67]
	v_mfma_f32_16x16x32_bf16 v[116:119], v[172:175], v[188:191], v[116:119]
	v_mfma_f32_16x16x32_bf16 v[108:111], v[180:183], v[188:191], v[108:111]
	v_mfma_f32_16x16x32_bf16 v[100:103], v[172:175], v[196:199], v[100:103]
	v_mfma_f32_16x16x32_bf16 v[92:95], v[180:183], v[196:199], v[92:95]
	v_mfma_f32_16x16x32_bf16 v[84:87], v[172:175], v[204:207], v[84:87]
	v_mfma_f32_16x16x32_bf16 v[76:79], v[180:183], v[204:207], v[76:79]
	v_mfma_f32_16x16x32_bf16 v[68:71], v[172:175], v[212:215], v[68:71]
	v_mfma_f32_16x16x32_bf16 v[64:67], v[180:183], v[212:215], v[64:67]
	s_barrier
	s_add_i32 s76, s69, s41
	v_lshl_add_u64 v[216:217], s[30:31], 0, v[130:131]
	s_mov_b32 m0, s76
	ds_read_b128 v[184:187], v155 offset:16384
	ds_read_b128 v[188:191], v155 offset:17408
	ds_read_b128 v[192:195], v155 offset:18432
	ds_read_b128 v[196:199], v155 offset:19456
	ds_read_b128 v[200:203], v155 offset:20480
	ds_read_b128 v[204:207], v155 offset:21504
	ds_read_b128 v[208:211], v155 offset:22528
	ds_read_b128 v[212:215], v155 offset:23552
	global_load_lds_dwordx4 v[216:217], off
	s_add_i32 m0, s76, 0x2000
	s_add_u32 s76, s30, 0x40000
	v_lshl_add_u64 v[218:219], s[30:31], 0, v[134:135]
	s_addc_u32 s77, s31, 0
	s_add_i32 s78, s71, s41
	global_load_lds_dwordx4 v[218:219], off
	v_lshl_add_u64 v[220:221], s[76:77], 0, v[130:131]
	s_mov_b32 m0, s78
	v_lshl_add_u64 v[222:223], s[34:35], 0, v[132:133]
	global_load_lds_dwordx4 v[220:221], off
	v_lshl_add_u64 v[220:221], s[76:77], 0, v[134:135]
	s_add_i32 m0, s78, 0x2000
	s_nop 0
	global_load_lds_dwordx4 v[220:221], off
	v_lshl_add_u64 v[220:221], s[34:35], 0, v[128:129]
	s_mov_b32 m0, s52
	s_nop 0
	global_load_lds_dwordx4 v[220:221], off
	s_mov_b32 m0, s53
	s_nop 0
	global_load_lds_dwordx4 v[222:223], off
	s_waitcnt vmcnt(8)
	s_waitcnt lgkmcnt(0)
	s_barrier
; #define PG8_STAGE(bufoff, gbase, voff) do { _Pragma("unroll") for (int _i = 0; _i < 2; ++_i) \
;         __builtin_amdgcn_global_load_lds((const unsigned*)((const char*)(gbase) + (voff)[_i]), (PG8_LAS unsigned*)(lds + (bufoff) + ldsw + _i * 8192), 16, 0, 0); } while (0)
; #define PG8_LDA(dst, b, h) do { _Pragma("unroll") for (int m = 0; m < 4; ++m) _Pragma("unroll") for (int k = 0; k < 2; ++k) dst[m][k] = *(const PG8_LAS bf16x8*)(lds + PG8_SA(b, h) + aoff + m * 2048 + k * 1024); } while (0)
; #define PG8_LDB(dst, b, h) do { _Pragma("unroll") for (int n = 0; n < 2; ++n) _Pragma("unroll") for (int k = 0; k < 2; ++k) dst[n][k] = *(const PG8_LAS bf16x8*)(lds + PG8_SB(b, h) + boff + n * 2048 + k * 1024); } while (0)
; #define PG8_MMA(ai, bj, At, Bt) do { __builtin_amdgcn_s_setprio(1); _Pragma("unroll") for (int m = 0; m < 4; ++m) _Pragma("unroll") for (int n = 0; n < 2; ++n) _Pragma("unroll") for (int k = 0; k < 2; ++k) \
;         acc[ai][bj][m][n] = __builtin_amdgcn_mfma_f32_16x16x32_bf16(Bt[n][k], At[m][k], acc[ai][bj][m][n], 0, 0, 0); __builtin_amdgcn_s_setprio(0); } while (0)
; #define PG8_WAIT_V(n) asm volatile("s_waitcnt vmcnt(" #n ")" ::: "memory")
; #define PG8_WAIT_L(n) asm volatile("s_waitcnt lgkmcnt(" #n ")" ::: "memory")
; #define PG8_BAR __builtin_amdgcn_s_barrier()
; #define PG8_SCHED __builtin_amdgcn_sched_barrier(0)
; template <class Epi, class Sched, bool ALIGN_EPI = false, bool SP2 = false>
; __device__ __forceinline__ void gemm_phase(PG8_LAS unsigned char* lds, const Gemm g, const Sched& S, const Epi& E, const int wave_s) {
;     ...
;             PG8_WAIT_V(8); PG8_WAIT_L(0); PG8_BAR; PG8_MMA(1, 0, At, B0); PG8_MMA(1, 1, At, B1); PG8_BAR; PG8_SCHED;
;             PG8_LDB(B0, 1, 0); PG8_LDB(B1, 1, 1); PG8_SCHED; PG8_LDA(At, 1, 0); PG8_STAGE(PG8_SA(0, 1), a2 + hstep, voffA);
;             PG8_WAIT_V(8); PG8_WAIT_L(0); PG8_BAR; PG8_MMA(0, 0, At, B0); PG8_MMA(0, 1, At, B1); PG8_BAR; PG8_SCHED;
	s_waitcnt lgkmcnt(0)
	v_mfma_f32_16x16x32_bf16 v[60:63], v[146:149], v[184:187], v[60:63]
	v_mfma_f32_16x16x32_bf16 v[56:59], v[160:163], v[184:187], v[56:59]
	v_mfma_f32_16x16x32_bf16 v[48:51], v[146:149], v[192:195], v[48:51]
	v_mfma_f32_16x16x32_bf16 v[40:43], v[160:163], v[192:195], v[40:43]
	v_mfma_f32_16x16x32_bf16 v[32:35], v[146:149], v[200:203], v[32:35]
	v_mfma_f32_16x16x32_bf16 v[24:27], v[160:163], v[200:203], v[24:27]
	v_mfma_f32_16x16x32_bf16 v[16:19], v[146:149], v[208:211], v[16:19]
	v_mfma_f32_16x16x32_bf16 v[8:11], v[160:163], v[208:211], v[8:11]
	v_mfma_f32_16x16x32_bf16 v[60:63], v[156:159], v[188:191], v[60:63]
	v_mfma_f32_16x16x32_bf16 v[56:59], v[164:167], v[188:191], v[56:59]
	v_mfma_f32_16x16x32_bf16 v[48:51], v[156:159], v[196:199], v[48:51]
	v_mfma_f32_16x16x32_bf16 v[40:43], v[164:167], v[196:199], v[40:43]
	v_mfma_f32_16x16x32_bf16 v[32:35], v[156:159], v[204:207], v[32:35]
	v_mfma_f32_16x16x32_bf16 v[24:27], v[164:167], v[204:207], v[24:27]
	v_mfma_f32_16x16x32_bf16 v[16:19], v[156:159], v[212:215], v[16:19]
	v_mfma_f32_16x16x32_bf16 v[8:11], v[164:167], v[212:215], v[8:11]
	v_mfma_f32_16x16x32_bf16 v[52:55], v[168:171], v[184:187], v[52:55]
	v_mfma_f32_16x16x32_bf16 v[44:47], v[176:179], v[184:187], v[44:47]
	v_mfma_f32_16x16x32_bf16 v[36:39], v[168:171], v[192:195], v[36:39]
	v_mfma_f32_16x16x32_bf16 v[28:31], v[176:179], v[192:195], v[28:31]
	v_mfma_f32_16x16x32_bf16 v[20:23], v[168:171], v[200:203], v[20:23]
	v_mfma_f32_16x16x32_bf16 v[12:15], v[176:179], v[200:203], v[12:15]
	v_mfma_f32_16x16x32_bf16 v[4:7], v[168:171], v[208:211], v[4:7]
	v_mfma_f32_16x16x32_bf16 v[0:3], v[176:179], v[208:211], v[0:3]
	v_mfma_f32_16x16x32_bf16 v[52:55], v[172:175], v[188:191], v[52:55]
	v_mfma_f32_16x16x32_bf16 v[44:47], v[180:183], v[188:191], v[44:47]
	v_mfma_f32_16x16x32_bf16 v[36:39], v[172:175], v[196:199], v[36:39]
	v_mfma_f32_16x16x32_bf16 v[28:31], v[180:183], v[196:199], v[28:31]
	v_mfma_f32_16x16x32_bf16 v[20:23], v[172:175], v[204:207], v[20:23]
	v_mfma_f32_16x16x32_bf16 v[12:15], v[180:183], v[204:207], v[12:15]
	v_mfma_f32_16x16x32_bf16 v[4:7], v[172:175], v[212:215], v[4:7]
	v_mfma_f32_16x16x32_bf16 v[0:3], v[180:183], v[212:215], v[0:3]
	s_barrier
	s_add_i32 s76, 0, 0x18000
	v_add_u32_e32 v136, s76, v152
	s_add_i32 s77, 0, 0x1c000
	ds_read_b128 v[146:149], v136
	ds_read_b128 v[156:159], v136 offset:1024
	ds_read_b128 v[160:163], v136 offset:2048
	ds_read_b128 v[164:167], v136 offset:3072
	v_add_u32_e32 v136, s77, v152
	ds_read_b128 v[168:171], v136
	ds_read_b128 v[172:175], v136 offset:1024
	ds_read_b128 v[176:179], v136 offset:2048
	ds_read_b128 v[180:183], v136 offset:3072
	s_add_u32 s34, s34, 0x40000
	s_addc_u32 s35, s35, 0
	s_mov_b32 m0, s54
	v_lshl_add_u64 v[224:225], s[34:35], 0, v[128:129]
	ds_read_b128 v[184:187], v155 offset:32768
	ds_read_b128 v[188:191], v155 offset:33792
	ds_read_b128 v[192:195], v155 offset:34816
	ds_read_b128 v[196:199], v155 offset:35840
	ds_read_b128 v[200:203], v155 offset:36864
	ds_read_b128 v[204:207], v155 offset:37888
	ds_read_b128 v[208:211], v155 offset:38912
	ds_read_b128 v[212:215], v155 offset:39936
	global_load_lds_dwordx4 v[224:225], off
	v_lshl_add_u64 v[224:225], s[34:35], 0, v[132:133]
	s_mov_b32 m0, s55
	s_nop 0
	global_load_lds_dwordx4 v[224:225], off
	s_waitcnt vmcnt(8)
	s_waitcnt lgkmcnt(0)
	s_barrier
	s_waitcnt lgkmcnt(0)
	v_mfma_f32_16x16x32_bf16 v[124:127], v[146:149], v[184:187], v[124:127]
	v_mfma_f32_16x16x32_bf16 v[120:123], v[160:163], v[184:187], v[120:123]
	v_mfma_f32_16x16x32_bf16 v[112:115], v[146:149], v[192:195], v[112:115]
	v_mfma_f32_16x16x32_bf16 v[104:107], v[160:163], v[192:195], v[104:107]
	v_mfma_f32_16x16x32_bf16 v[96:99], v[146:149], v[200:203], v[96:99]
	v_mfma_f32_16x16x32_bf16 v[88:91], v[160:163], v[200:203], v[88:91]
	v_mfma_f32_16x16x32_bf16 v[80:83], v[146:149], v[208:211], v[80:83]
	v_mfma_f32_16x16x32_bf16 v[72:75], v[160:163], v[208:211], v[72:75]
	v_mfma_f32_16x16x32_bf16 v[124:127], v[156:159], v[188:191], v[124:127]
	v_mfma_f32_16x16x32_bf16 v[120:123], v[164:167], v[188:191], v[120:123]
	v_mfma_f32_16x16x32_bf16 v[112:115], v[156:159], v[196:199], v[112:115]
	v_mfma_f32_16x16x32_bf16 v[104:107], v[164:167], v[196:199], v[104:107]
	v_mfma_f32_16x16x32_bf16 v[96:99], v[156:159], v[204:207], v[96:99]
	v_mfma_f32_16x16x32_bf16 v[88:91], v[164:167], v[204:207], v[88:91]
	v_mfma_f32_16x16x32_bf16 v[80:83], v[156:159], v[212:215], v[80:83]
	v_mfma_f32_16x16x32_bf16 v[72:75], v[164:167], v[212:215], v[72:75]
	v_mfma_f32_16x16x32_bf16 v[116:119], v[168:171], v[184:187], v[116:119]
	v_mfma_f32_16x16x32_bf16 v[108:111], v[176:179], v[184:187], v[108:111]
	v_mfma_f32_16x16x32_bf16 v[100:103], v[168:171], v[192:195], v[100:103]
	v_mfma_f32_16x16x32_bf16 v[92:95], v[176:179], v[192:195], v[92:95]
	v_mfma_f32_16x16x32_bf16 v[84:87], v[168:171], v[200:203], v[84:87]
	v_mfma_f32_16x16x32_bf16 v[76:79], v[176:179], v[200:203], v[76:79]
	v_mfma_f32_16x16x32_bf16 v[68:71], v[168:171], v[208:211], v[68:71]
	v_mfma_f32_16x16x32_bf16 v[64:67], v[176:179], v[208:211], v[64:67]
	v_mfma_f32_16x16x32_bf16 v[116:119], v[172:175], v[188:191], v[116:119]
	v_mfma_f32_16x16x32_bf16 v[108:111], v[180:183], v[188:191], v[108:111]
	v_mfma_f32_16x16x32_bf16 v[100:103], v[172:175], v[196:199], v[100:103]
	v_mfma_f32_16x16x32_bf16 v[92:95], v[180:183], v[196:199], v[92:95]
	v_mfma_f32_16x16x32_bf16 v[84:87], v[172:175], v[204:207], v[84:87]
	v_mfma_f32_16x16x32_bf16 v[76:79], v[180:183], v[204:207], v[76:79]
	v_mfma_f32_16x16x32_bf16 v[68:71], v[172:175], v[212:215], v[68:71]
	v_mfma_f32_16x16x32_bf16 v[64:67], v[180:183], v[212:215], v[64:67]
	s_barrier
; #define PG8_STAGE(bufoff, gbase, voff) do { _Pragma("unroll") for (int _i = 0; _i < 2; ++_i) \
;         __builtin_amdgcn_global_load_lds((const unsigned*)((const char*)(gbase) + (voff)[_i]), (PG8_LAS unsigned*)(lds + (bufoff) + ldsw + _i * 8192), 16, 0, 0); } while (0)
; #define PG8_LDA(dst, b, h) do { _Pragma("unroll") for (int m = 0; m < 4; ++m) _Pragma("unroll") for (int k = 0; k < 2; ++k) dst[m][k] = *(const PG8_LAS bf16x8*)(lds + PG8_SA(b, h) + aoff + m * 2048 + k * 1024); } while (0)
; #define PG8_MMA(ai, bj, At, Bt) do { __builtin_amdgcn_s_setprio(1); _Pragma("unroll") for (int m = 0; m < 4; ++m) _Pragma("unroll") for (int n = 0; n < 2; ++n) _Pragma("unroll") for (int k = 0; k < 2; ++k) \
;         acc[ai][bj][m][n] = __builtin_amdgcn_mfma_f32_16x16x32_bf16(Bt[n][k], At[m][k], acc[ai][bj][m][n], 0, 0, 0); __builtin_amdgcn_s_setprio(0); } while (0)
; #define PG8_WAIT_V(n) asm volatile("s_waitcnt vmcnt(" #n ")" ::: "memory")
; #define PG8_WAIT_L(n) asm volatile("s_waitcnt lgkmcnt(" #n ")" ::: "memory")
; #define PG8_BAR __builtin_amdgcn_s_barrier()
; #define PG8_SCHED __builtin_amdgcn_sched_barrier(0)
; template <class Epi, class Sched, bool ALIGN_EPI = false, bool SP2 = false>
; __device__ __forceinline__ void gemm_phase(PG8_LAS unsigned char* lds, const Gemm g, const Sched& S, const Epi& E, const int wave_s) {
;     ...
;             PG8_LDA(At, 1, 1); PG8_STAGE(PG8_SB(1, 0), b3, voffB); PG8_STAGE(PG8_SB(1, 1), b3 + hstep, voffB); PG8_STAGE(PG8_SA(1, 0), a3, voffA);
;             PG8_WAIT_V(8); PG8_WAIT_L(0); PG8_BAR; PG8_MMA(1, 0, At, B0); PG8_MMA(1, 1, At, B1); PG8_BAR; PG8_SCHED;
	s_add_i32 s34, s76, s41
	v_lshl_add_u64 v[216:217], v[216:217], 0, s[8:9]
	s_mov_b32 m0, s34
	ds_read_b128 v[184:187], v155 offset:49152
	ds_read_b128 v[188:191], v155 offset:50176
	ds_read_b128 v[192:195], v155 offset:51200
	ds_read_b128 v[196:199], v155 offset:52224
	ds_read_b128 v[200:203], v155 offset:53248
	ds_read_b128 v[204:207], v155 offset:54272
	ds_read_b128 v[208:211], v155 offset:55296
	ds_read_b128 v[212:215], v155 offset:56320
	global_load_lds_dwordx4 v[216:217], off
	s_add_i32 m0, s34, 0x2000
	s_add_u32 s30, s30, 0x40080
	v_lshl_add_u64 v[216:217], v[218:219], 0, s[8:9]
	s_addc_u32 s31, s31, 0
	s_add_i32 s34, s77, s41
	global_load_lds_dwordx4 v[216:217], off
	v_lshl_add_u64 v[216:217], s[30:31], 0, v[130:131]
	s_mov_b32 m0, s34
	s_nop 0
	global_load_lds_dwordx4 v[216:217], off
	v_lshl_add_u64 v[216:217], s[30:31], 0, v[134:135]
	s_add_i32 m0, s34, 0x2000
	s_nop 0
	global_load_lds_dwordx4 v[216:217], off
	v_lshl_add_u64 v[216:217], v[220:221], 0, s[8:9]
	s_mov_b32 m0, s65
	s_nop 0
	global_load_lds_dwordx4 v[216:217], off
	v_lshl_add_u64 v[216:217], v[222:223], 0, s[8:9]
	s_mov_b32 m0, s66
	s_nop 0
	global_load_lds_dwordx4 v[216:217], off
	s_waitcnt vmcnt(8)
	s_waitcnt lgkmcnt(0)
	s_barrier
	s_waitcnt lgkmcnt(0)
	v_mfma_f32_16x16x32_bf16 v[60:63], v[146:149], v[184:187], v[60:63]
	v_mfma_f32_16x16x32_bf16 v[56:59], v[160:163], v[184:187], v[56:59]
	v_mfma_f32_16x16x32_bf16 v[48:51], v[146:149], v[192:195], v[48:51]
	v_mfma_f32_16x16x32_bf16 v[40:43], v[160:163], v[192:195], v[40:43]
	v_mfma_f32_16x16x32_bf16 v[32:35], v[146:149], v[200:203], v[32:35]
	v_mfma_f32_16x16x32_bf16 v[24:27], v[160:163], v[200:203], v[24:27]
	v_mfma_f32_16x16x32_bf16 v[16:19], v[146:149], v[208:211], v[16:19]
	v_mfma_f32_16x16x32_bf16 v[8:11], v[160:163], v[208:211], v[8:11]
	v_mfma_f32_16x16x32_bf16 v[60:63], v[156:159], v[188:191], v[60:63]
	v_mfma_f32_16x16x32_bf16 v[56:59], v[164:167], v[188:191], v[56:59]
	v_mfma_f32_16x16x32_bf16 v[48:51], v[156:159], v[196:199], v[48:51]
	v_mfma_f32_16x16x32_bf16 v[40:43], v[164:167], v[196:199], v[40:43]
	v_mfma_f32_16x16x32_bf16 v[32:35], v[156:159], v[204:207], v[32:35]
	v_mfma_f32_16x16x32_bf16 v[24:27], v[164:167], v[204:207], v[24:27]
	v_mfma_f32_16x16x32_bf16 v[16:19], v[156:159], v[212:215], v[16:19]
	v_mfma_f32_16x16x32_bf16 v[8:11], v[164:167], v[212:215], v[8:11]
	v_mfma_f32_16x16x32_bf16 v[52:55], v[168:171], v[184:187], v[52:55]
	v_mfma_f32_16x16x32_bf16 v[44:47], v[176:179], v[184:187], v[44:47]
	v_mfma_f32_16x16x32_bf16 v[36:39], v[168:171], v[192:195], v[36:39]
	v_mfma_f32_16x16x32_bf16 v[28:31], v[176:179], v[192:195], v[28:31]
	v_mfma_f32_16x16x32_bf16 v[20:23], v[168:171], v[200:203], v[20:23]
	v_mfma_f32_16x16x32_bf16 v[12:15], v[176:179], v[200:203], v[12:15]
	v_mfma_f32_16x16x32_bf16 v[4:7], v[168:171], v[208:211], v[4:7]
	v_mfma_f32_16x16x32_bf16 v[0:3], v[176:179], v[208:211], v[0:3]
	v_mfma_f32_16x16x32_bf16 v[52:55], v[172:175], v[188:191], v[52:55]
	v_mfma_f32_16x16x32_bf16 v[44:47], v[180:183], v[188:191], v[44:47]
	v_mfma_f32_16x16x32_bf16 v[36:39], v[172:175], v[196:199], v[36:39]
	v_mfma_f32_16x16x32_bf16 v[28:31], v[180:183], v[196:199], v[28:31]
	v_mfma_f32_16x16x32_bf16 v[20:23], v[172:175], v[204:207], v[20:23]
	v_mfma_f32_16x16x32_bf16 v[12:15], v[180:183], v[204:207], v[12:15]
	v_mfma_f32_16x16x32_bf16 v[4:7], v[172:175], v[212:215], v[4:7]
	v_mfma_f32_16x16x32_bf16 v[0:3], v[180:183], v[212:215], v[0:3]
	s_barrier
	s_add_i32 s75, s75, 2
	s_add_u32 s28, s28, 0x100
	s_addc_u32 s29, s29, 0
	s_add_u32 s73, s73, 0x100
	s_addc_u32 s74, s74, 0
	s_cmp_gt_u32 s75, 13
	s_cbranch_scc0 .LBB0_250
	s_and_b64 vcc, exec, s[10:11]
	s_cbranch_vccz .LBB0_253
	s_barrier

; #define PG8_STAGE(bufoff, gbase, voff) do { _Pragma("unroll") for (int _i = 0; _i < 2; ++_i) \
;         __builtin_amdgcn_global_load_lds((const unsigned*)((const char*)(gbase) + (voff)[_i]), (PG8_LAS unsigned*)(lds + (bufoff) + ldsw + _i * 8192), 16, 0, 0); } while (0)
; #define PG8_LDA(dst, b, h) do { _Pragma("unroll") for (int m = 0; m < 4; ++m) _Pragma("unroll") for (int k = 0; k < 2; ++k) dst[m][k] = *(const PG8_LAS bf16x8*)(lds + PG8_SA(b, h) + aoff + m * 2048 + k * 1024); } while (0)
; #define PG8_LDB(dst, b, h) do { _Pragma("unroll") for (int n = 0; n < 2; ++n) _Pragma("unroll") for (int k = 0; k < 2; ++k) dst[n][k] = *(const PG8_LAS bf16x8*)(lds + PG8_SB(b, h) + boff + n * 2048 + k * 1024); } while (0)
; #define PG8_MMA(ai, bj, At, Bt) do { __builtin_amdgcn_s_setprio(1); _Pragma("unroll") for (int m = 0; m < 4; ++m) _Pragma("unroll") for (int n = 0; n < 2; ++n) _Pragma("unroll") for (int k = 0; k < 2; ++k) \
;         acc[ai][bj][m][n] = __builtin_amdgcn_mfma_f32_16x16x32_bf16(Bt[n][k], At[m][k], acc[ai][bj][m][n], 0, 0, 0); __builtin_amdgcn_s_setprio(0); } while (0)
; #define PG8_WAIT_V(n) asm volatile("s_waitcnt vmcnt(" #n ")" ::: "memory")
; #define PG8_WAIT_L(n) asm volatile("s_waitcnt lgkmcnt(" #n ")" ::: "memory")
; #define PG8_BAR __builtin_amdgcn_s_barrier()
; #define PG8_SCHED __builtin_amdgcn_sched_barrier(0)
; template <class Epi, class Sched, bool ALIGN_EPI = false, bool SP2 = false>
; __device__ __forceinline__ void gemm_phase(PG8_LAS unsigned char* lds, const Gemm g, const Sched& S, const Epi& E, const int wave_s) {
;     ...
;             PG8_LDB(B0, 0, 0); PG8_LDB(B1, 0, 1); PG8_SCHED; PG8_LDA(At, 0, 0); PG8_STAGE(PG8_SA(1, 1), a1 + hstep, voffA);
;             PG8_WAIT_V(8); PG8_WAIT_L(0); PG8_BAR; PG8_MMA(0, 0, At, B0); PG8_MMA(0, 1, At, B1); PG8_BAR; PG8_SCHED;
;             PG8_LDA(At, 0, 1); PG8_STAGE(PG8_SB(0, 0), b2, voffB); PG8_STAGE(PG8_SB(0, 1), b2 + hstep, voffB); PG8_STAGE(PG8_SA(0, 0), a2, voffA);
.LBB0_469:
	ds_read_b128 v[128:131], v207
	ds_read_b128 v[132:135], v207 offset:1024
	ds_read_b128 v[136:139], v207 offset:2048
	ds_read_b128 v[140:143], v207 offset:3072
	ds_read_b128 v[144:147], v208
	ds_read_b128 v[148:151], v208 offset:1024
	ds_read_b128 v[152:155], v208 offset:2048
	ds_read_b128 v[156:159], v208 offset:3072
	s_add_u32 s26, s6, 0xfffc0080
	s_addc_u32 s27, s7, -1
	s_cmp_eq_u32 s53, 12
	s_cselect_b32 s29, s1, s27
	s_cselect_b32 s28, s17, s26
	s_cselect_b32 s27, s15, s52
	s_cselect_b32 s26, s50, s51
	v_lshl_add_u64 v[216:217], s[6:7], 0, v[184:185]
	s_add_i32 m0, s3, 0xc000
	ds_read_b128 v[160:163], v209
	ds_read_b128 v[164:167], v209 offset:1024
	ds_read_b128 v[168:171], v209 offset:2048
	ds_read_b128 v[172:175], v209 offset:3072
	ds_read_b128 v[192:195], v209 offset:4096
	ds_read_b128 v[196:199], v209 offset:5120
	ds_read_b128 v[200:203], v209 offset:6144
	ds_read_b128 v[212:215], v209 offset:7168
	global_load_lds_dwordx4 v[216:217], off
	v_lshl_add_u64 v[216:217], s[6:7], 0, v[186:187]
	s_add_i32 m0, s3, 0xe000
	s_nop 0
	global_load_lds_dwordx4 v[216:217], off
	s_waitcnt vmcnt(8)
	s_waitcnt lgkmcnt(0)
	s_barrier
	s_waitcnt lgkmcnt(0)
	v_mfma_f32_16x16x32_bf16 v[124:127], v[128:131], v[160:163], v[124:127]
	v_mfma_f32_16x16x32_bf16 v[120:123], v[136:139], v[160:163], v[120:123]
	v_mfma_f32_16x16x32_bf16 v[108:111], v[128:131], v[168:171], v[108:111]
	v_mfma_f32_16x16x32_bf16 v[104:107], v[136:139], v[168:171], v[104:107]
	v_mfma_f32_16x16x32_bf16 v[92:95], v[128:131], v[192:195], v[92:95]
	v_mfma_f32_16x16x32_bf16 v[88:91], v[136:139], v[192:195], v[88:91]
	v_mfma_f32_16x16x32_bf16 v[76:79], v[128:131], v[200:203], v[76:79]
	v_mfma_f32_16x16x32_bf16 v[72:75], v[136:139], v[200:203], v[72:75]
	v_mfma_f32_16x16x32_bf16 v[124:127], v[132:135], v[164:167], v[124:127]
	v_mfma_f32_16x16x32_bf16 v[120:123], v[140:143], v[164:167], v[120:123]
	v_mfma_f32_16x16x32_bf16 v[108:111], v[132:135], v[172:175], v[108:111]
	v_mfma_f32_16x16x32_bf16 v[104:107], v[140:143], v[172:175], v[104:107]
	v_mfma_f32_16x16x32_bf16 v[92:95], v[132:135], v[196:199], v[92:95]
	v_mfma_f32_16x16x32_bf16 v[88:91], v[140:143], v[196:199], v[88:91]
	v_mfma_f32_16x16x32_bf16 v[76:79], v[132:135], v[212:215], v[76:79]
	v_mfma_f32_16x16x32_bf16 v[72:75], v[140:143], v[212:215], v[72:75]
	v_mfma_f32_16x16x32_bf16 v[116:119], v[144:147], v[160:163], v[116:119]
	v_mfma_f32_16x16x32_bf16 v[112:115], v[152:155], v[160:163], v[112:115]
	v_mfma_f32_16x16x32_bf16 v[100:103], v[144:147], v[168:171], v[100:103]
	v_mfma_f32_16x16x32_bf16 v[96:99], v[152:155], v[168:171], v[96:99]
	v_mfma_f32_16x16x32_bf16 v[84:87], v[144:147], v[192:195], v[84:87]
	v_mfma_f32_16x16x32_bf16 v[80:83], v[152:155], v[192:195], v[80:83]
	v_mfma_f32_16x16x32_bf16 v[68:71], v[144:147], v[200:203], v[68:71]
	v_mfma_f32_16x16x32_bf16 v[64:67], v[152:155], v[200:203], v[64:67]
	v_mfma_f32_16x16x32_bf16 v[116:119], v[148:151], v[164:167], v[116:119]
	v_mfma_f32_16x16x32_bf16 v[112:115], v[156:159], v[164:167], v[112:115]
	v_mfma_f32_16x16x32_bf16 v[100:103], v[148:151], v[172:175], v[100:103]
	v_mfma_f32_16x16x32_bf16 v[96:99], v[156:159], v[172:175], v[96:99]
	v_mfma_f32_16x16x32_bf16 v[84:87], v[148:151], v[196:199], v[84:87]
	v_mfma_f32_16x16x32_bf16 v[80:83], v[156:159], v[196:199], v[80:83]
	v_mfma_f32_16x16x32_bf16 v[68:71], v[148:151], v[212:215], v[68:71]
	v_mfma_f32_16x16x32_bf16 v[64:67], v[156:159], v[212:215], v[64:67]
	s_barrier
	s_add_i32 s54, s48, s30
	v_lshl_add_u64 v[216:217], s[26:27], 0, v[178:179]
	s_mov_b32 m0, s54
	ds_read_b128 v[160:163], v209 offset:16384
	ds_read_b128 v[164:167], v209 offset:17408
	ds_read_b128 v[168:171], v209 offset:18432
	ds_read_b128 v[172:175], v209 offset:19456
	ds_read_b128 v[192:195], v209 offset:20480
	ds_read_b128 v[196:199], v209 offset:21504
	ds_read_b128 v[200:203], v209 offset:22528
	ds_read_b128 v[212:215], v209 offset:23552
	global_load_lds_dwordx4 v[216:217], off
	s_add_i32 m0, s54, 0x2000
	s_add_u32 s54, s26, 0x40000
	v_lshl_add_u64 v[218:219], s[26:27], 0, v[182:183]
	s_addc_u32 s55, s27, 0
	s_add_i32 s58, s49, s30
	global_load_lds_dwordx4 v[218:219], off
	v_lshl_add_u64 v[220:221], s[54:55], 0, v[178:179]
	s_mov_b32 m0, s58
	v_lshl_add_u64 v[222:223], s[28:29], 0, v[180:181]
	global_load_lds_dwordx4 v[220:221], off
	v_lshl_add_u64 v[220:221], s[54:55], 0, v[182:183]
	s_add_i32 m0, s58, 0x2000
	s_nop 0
	global_load_lds_dwordx4 v[220:221], off
	v_lshl_add_u64 v[220:221], s[28:29], 0, v[176:177]
	s_mov_b32 m0, s3
	s_nop 0
	global_load_lds_dwordx4 v[220:221], off
	s_mov_b32 m0, s31
	s_nop 0
	global_load_lds_dwordx4 v[222:223], off
	s_waitcnt vmcnt(8)
	s_waitcnt lgkmcnt(0)
	s_barrier
; #define PG8_STAGE(bufoff, gbase, voff) do { _Pragma("unroll") for (int _i = 0; _i < 2; ++_i) \
;         __builtin_amdgcn_global_load_lds((const unsigned*)((const char*)(gbase) + (voff)[_i]), (PG8_LAS unsigned*)(lds + (bufoff) + ldsw + _i * 8192), 16, 0, 0); } while (0)
; #define PG8_LDA(dst, b, h) do { _Pragma("unroll") for (int m = 0; m < 4; ++m) _Pragma("unroll") for (int k = 0; k < 2; ++k) dst[m][k] = *(const PG8_LAS bf16x8*)(lds + PG8_SA(b, h) + aoff + m * 2048 + k * 1024); } while (0)
; #define PG8_LDB(dst, b, h) do { _Pragma("unroll") for (int n = 0; n < 2; ++n) _Pragma("unroll") for (int k = 0; k < 2; ++k) dst[n][k] = *(const PG8_LAS bf16x8*)(lds + PG8_SB(b, h) + boff + n * 2048 + k * 1024); } while (0)
; #define PG8_MMA(ai, bj, At, Bt) do { __builtin_amdgcn_s_setprio(1); _Pragma("unroll") for (int m = 0; m < 4; ++m) _Pragma("unroll") for (int n = 0; n < 2; ++n) _Pragma("unroll") for (int k = 0; k < 2; ++k) \
;         acc[ai][bj][m][n] = __builtin_amdgcn_mfma_f32_16x16x32_bf16(Bt[n][k], At[m][k], acc[ai][bj][m][n], 0, 0, 0); __builtin_amdgcn_s_setprio(0); } while (0)
; #define PG8_WAIT_V(n) asm volatile("s_waitcnt vmcnt(" #n ")" ::: "memory")
; #define PG8_WAIT_L(n) asm volatile("s_waitcnt lgkmcnt(" #n ")" ::: "memory")
; #define PG8_BAR __builtin_amdgcn_s_barrier()
; #define PG8_SCHED __builtin_amdgcn_sched_barrier(0)
; template <class Epi, class Sched, bool ALIGN_EPI = false, bool SP2 = false>
; __device__ __forceinline__ void gemm_phase(PG8_LAS unsigned char* lds, const Gemm g, const Sched& S, const Epi& E, const int wave_s) {
;     ...
;             PG8_WAIT_V(8); PG8_WAIT_L(0); PG8_BAR; PG8_MMA(1, 0, At, B0); PG8_MMA(1, 1, At, B1); PG8_BAR; PG8_SCHED;
;             PG8_LDB(B0, 1, 0); PG8_LDB(B1, 1, 1); PG8_SCHED; PG8_LDA(At, 1, 0); PG8_STAGE(PG8_SA(0, 1), a2 + hstep, voffA);
;             PG8_WAIT_V(8); PG8_WAIT_L(0); PG8_BAR; PG8_MMA(0, 0, At, B0); PG8_MMA(0, 1, At, B1); PG8_BAR; PG8_SCHED;
	s_waitcnt lgkmcnt(0)
	v_mfma_f32_16x16x32_bf16 v[60:63], v[128:131], v[160:163], v[60:63]
	v_mfma_f32_16x16x32_bf16 v[56:59], v[136:139], v[160:163], v[56:59]
	v_mfma_f32_16x16x32_bf16 v[44:47], v[128:131], v[168:171], v[44:47]
	v_mfma_f32_16x16x32_bf16 v[40:43], v[136:139], v[168:171], v[40:43]
	v_mfma_f32_16x16x32_bf16 v[28:31], v[128:131], v[192:195], v[28:31]
	v_mfma_f32_16x16x32_bf16 v[24:27], v[136:139], v[192:195], v[24:27]
	v_mfma_f32_16x16x32_bf16 v[12:15], v[128:131], v[200:203], v[12:15]
	v_mfma_f32_16x16x32_bf16 v[8:11], v[136:139], v[200:203], v[8:11]
	v_mfma_f32_16x16x32_bf16 v[60:63], v[132:135], v[164:167], v[60:63]
	v_mfma_f32_16x16x32_bf16 v[56:59], v[140:143], v[164:167], v[56:59]
	v_mfma_f32_16x16x32_bf16 v[44:47], v[132:135], v[172:175], v[44:47]
	v_mfma_f32_16x16x32_bf16 v[40:43], v[140:143], v[172:175], v[40:43]
	v_mfma_f32_16x16x32_bf16 v[28:31], v[132:135], v[196:199], v[28:31]
	v_mfma_f32_16x16x32_bf16 v[24:27], v[140:143], v[196:199], v[24:27]
	v_mfma_f32_16x16x32_bf16 v[12:15], v[132:135], v[212:215], v[12:15]
	v_mfma_f32_16x16x32_bf16 v[8:11], v[140:143], v[212:215], v[8:11]
	v_mfma_f32_16x16x32_bf16 v[52:55], v[144:147], v[160:163], v[52:55]
	v_mfma_f32_16x16x32_bf16 v[48:51], v[152:155], v[160:163], v[48:51]
	v_mfma_f32_16x16x32_bf16 v[36:39], v[144:147], v[168:171], v[36:39]
	v_mfma_f32_16x16x32_bf16 v[32:35], v[152:155], v[168:171], v[32:35]
	v_mfma_f32_16x16x32_bf16 v[20:23], v[144:147], v[192:195], v[20:23]
	v_mfma_f32_16x16x32_bf16 v[16:19], v[152:155], v[192:195], v[16:19]
	v_mfma_f32_16x16x32_bf16 v[4:7], v[144:147], v[200:203], v[4:7]
	v_mfma_f32_16x16x32_bf16 v[0:3], v[152:155], v[200:203], v[0:3]
	v_mfma_f32_16x16x32_bf16 v[52:55], v[148:151], v[164:167], v[52:55]
	v_mfma_f32_16x16x32_bf16 v[48:51], v[156:159], v[164:167], v[48:51]
	v_mfma_f32_16x16x32_bf16 v[36:39], v[148:151], v[172:175], v[36:39]
	v_mfma_f32_16x16x32_bf16 v[32:35], v[156:159], v[172:175], v[32:35]
	v_mfma_f32_16x16x32_bf16 v[20:23], v[148:151], v[196:199], v[20:23]
	v_mfma_f32_16x16x32_bf16 v[16:19], v[156:159], v[196:199], v[16:19]
	v_mfma_f32_16x16x32_bf16 v[4:7], v[148:151], v[212:215], v[4:7]
	v_mfma_f32_16x16x32_bf16 v[0:3], v[156:159], v[212:215], v[0:3]
	s_barrier
	s_add_i32 s54, 0, 0x18000
	s_add_i32 s55, 0, 0x1c000
	v_add_u32_e32 v140, s54, v206
	v_add_u32_e32 v156, s55, v206
	ds_read_b128 v[128:131], v140
	ds_read_b128 v[132:135], v140 offset:1024
	ds_read_b128 v[136:139], v140 offset:2048
	ds_read_b128 v[140:143], v140 offset:3072
	ds_read_b128 v[144:147], v156
	ds_read_b128 v[148:151], v156 offset:1024
	ds_read_b128 v[152:155], v156 offset:2048
	ds_read_b128 v[156:159], v156 offset:3072
	s_add_u32 s28, s28, 0x40000
	s_addc_u32 s29, s29, 0
	s_mov_b32 m0, s33
	v_lshl_add_u64 v[224:225], s[28:29], 0, v[176:177]
	ds_read_b128 v[160:163], v209 offset:32768
	ds_read_b128 v[164:167], v209 offset:33792
	ds_read_b128 v[168:171], v209 offset:34816
	ds_read_b128 v[172:175], v209 offset:35840
	ds_read_b128 v[192:195], v209 offset:36864
	ds_read_b128 v[196:199], v209 offset:37888
	ds_read_b128 v[200:203], v209 offset:38912
	ds_read_b128 v[212:215], v209 offset:39936
	global_load_lds_dwordx4 v[224:225], off
	v_lshl_add_u64 v[224:225], s[28:29], 0, v[180:181]
	s_mov_b32 m0, s34
	s_nop 0
	global_load_lds_dwordx4 v[224:225], off
	s_waitcnt vmcnt(8)
	s_waitcnt lgkmcnt(0)
	s_barrier
	s_waitcnt lgkmcnt(0)
	v_mfma_f32_16x16x32_bf16 v[124:127], v[128:131], v[160:163], v[124:127]
	v_mfma_f32_16x16x32_bf16 v[120:123], v[136:139], v[160:163], v[120:123]
	v_mfma_f32_16x16x32_bf16 v[108:111], v[128:131], v[168:171], v[108:111]
	v_mfma_f32_16x16x32_bf16 v[104:107], v[136:139], v[168:171], v[104:107]
	v_mfma_f32_16x16x32_bf16 v[92:95], v[128:131], v[192:195], v[92:95]
	v_mfma_f32_16x16x32_bf16 v[88:91], v[136:139], v[192:195], v[88:91]
	v_mfma_f32_16x16x32_bf16 v[76:79], v[128:131], v[200:203], v[76:79]
	v_mfma_f32_16x16x32_bf16 v[72:75], v[136:139], v[200:203], v[72:75]
	v_mfma_f32_16x16x32_bf16 v[124:127], v[132:135], v[164:167], v[124:127]
	v_mfma_f32_16x16x32_bf16 v[120:123], v[140:143], v[164:167], v[120:123]
	v_mfma_f32_16x16x32_bf16 v[108:111], v[132:135], v[172:175], v[108:111]
	v_mfma_f32_16x16x32_bf16 v[104:107], v[140:143], v[172:175], v[104:107]
	v_mfma_f32_16x16x32_bf16 v[92:95], v[132:135], v[196:199], v[92:95]
	v_mfma_f32_16x16x32_bf16 v[88:91], v[140:143], v[196:199], v[88:91]
	v_mfma_f32_16x16x32_bf16 v[76:79], v[132:135], v[212:215], v[76:79]
	v_mfma_f32_16x16x32_bf16 v[72:75], v[140:143], v[212:215], v[72:75]
	v_mfma_f32_16x16x32_bf16 v[116:119], v[144:147], v[160:163], v[116:119]
	v_mfma_f32_16x16x32_bf16 v[112:115], v[152:155], v[160:163], v[112:115]
	v_mfma_f32_16x16x32_bf16 v[100:103], v[144:147], v[168:171], v[100:103]
	v_mfma_f32_16x16x32_bf16 v[96:99], v[152:155], v[168:171], v[96:99]
	v_mfma_f32_16x16x32_bf16 v[84:87], v[144:147], v[192:195], v[84:87]
	v_mfma_f32_16x16x32_bf16 v[80:83], v[152:155], v[192:195], v[80:83]
	v_mfma_f32_16x16x32_bf16 v[68:71], v[144:147], v[200:203], v[68:71]
	v_mfma_f32_16x16x32_bf16 v[64:67], v[152:155], v[200:203], v[64:67]
	v_mfma_f32_16x16x32_bf16 v[116:119], v[148:151], v[164:167], v[116:119]
	v_mfma_f32_16x16x32_bf16 v[112:115], v[156:159], v[164:167], v[112:115]
	v_mfma_f32_16x16x32_bf16 v[100:103], v[148:151], v[172:175], v[100:103]
	v_mfma_f32_16x16x32_bf16 v[96:99], v[156:159], v[172:175], v[96:99]
	v_mfma_f32_16x16x32_bf16 v[84:87], v[148:151], v[196:199], v[84:87]
	v_mfma_f32_16x16x32_bf16 v[80:83], v[156:159], v[196:199], v[80:83]
	v_mfma_f32_16x16x32_bf16 v[68:71], v[148:151], v[212:215], v[68:71]
	v_mfma_f32_16x16x32_bf16 v[64:67], v[156:159], v[212:215], v[64:67]
	s_barrier
; #define PG8_STAGE(bufoff, gbase, voff) do { _Pragma("unroll") for (int _i = 0; _i < 2; ++_i) \
;         __builtin_amdgcn_global_load_lds((const unsigned*)((const char*)(gbase) + (voff)[_i]), (PG8_LAS unsigned*)(lds + (bufoff) + ldsw + _i * 8192), 16, 0, 0); } while (0)
; #define PG8_LDA(dst, b, h) do { _Pragma("unroll") for (int m = 0; m < 4; ++m) _Pragma("unroll") for (int k = 0; k < 2; ++k) dst[m][k] = *(const PG8_LAS bf16x8*)(lds + PG8_SA(b, h) + aoff + m * 2048 + k * 1024); } while (0)
; #define PG8_MMA(ai, bj, At, Bt) do { __builtin_amdgcn_s_setprio(1); _Pragma("unroll") for (int m = 0; m < 4; ++m) _Pragma("unroll") for (int n = 0; n < 2; ++n) _Pragma("unroll") for (int k = 0; k < 2; ++k) \
;         acc[ai][bj][m][n] = __builtin_amdgcn_mfma_f32_16x16x32_bf16(Bt[n][k], At[m][k], acc[ai][bj][m][n], 0, 0, 0); __builtin_amdgcn_s_setprio(0); } while (0)
; #define PG8_WAIT_V(n) asm volatile("s_waitcnt vmcnt(" #n ")" ::: "memory")
; #define PG8_WAIT_L(n) asm volatile("s_waitcnt lgkmcnt(" #n ")" ::: "memory")
; #define PG8_BAR __builtin_amdgcn_s_barrier()
; #define PG8_SCHED __builtin_amdgcn_sched_barrier(0)
; template <class Epi, class Sched, bool ALIGN_EPI = false, bool SP2 = false>
; __device__ __forceinline__ void gemm_phase(PG8_LAS unsigned char* lds, const Gemm g, const Sched& S, const Epi& E, const int wave_s) {
;     ...
;             PG8_LDA(At, 1, 1); PG8_STAGE(PG8_SB(1, 0), b3, voffB); PG8_STAGE(PG8_SB(1, 1), b3 + hstep, voffB); PG8_STAGE(PG8_SA(1, 0), a3, voffA);
;             PG8_WAIT_V(8); PG8_WAIT_L(0); PG8_BAR; PG8_MMA(1, 0, At, B0); PG8_MMA(1, 1, At, B1); PG8_BAR; PG8_SCHED;
	s_add_i32 s28, s54, s30
	v_lshl_add_u64 v[216:217], v[216:217], 0, s[10:11]
	s_mov_b32 m0, s28
	ds_read_b128 v[160:163], v209 offset:49152
	ds_read_b128 v[164:167], v209 offset:50176
	ds_read_b128 v[168:171], v209 offset:51200
	ds_read_b128 v[172:175], v209 offset:52224
	ds_read_b128 v[192:195], v209 offset:53248
	ds_read_b128 v[196:199], v209 offset:54272
	ds_read_b128 v[200:203], v209 offset:55296
	ds_read_b128 v[212:215], v209 offset:56320
	global_load_lds_dwordx4 v[216:217], off
	s_add_i32 m0, s28, 0x2000
	s_add_u32 s26, s26, 0x40080
	v_lshl_add_u64 v[216:217], v[218:219], 0, s[10:11]
	s_addc_u32 s27, s27, 0
	s_add_i32 s28, s55, s30
	global_load_lds_dwordx4 v[216:217], off
	v_lshl_add_u64 v[216:217], s[26:27], 0, v[178:179]
	s_mov_b32 m0, s28
	s_nop 0
	global_load_lds_dwordx4 v[216:217], off
	v_lshl_add_u64 v[216:217], s[26:27], 0, v[182:183]
	s_add_i32 m0, s28, 0x2000
	s_nop 0
	global_load_lds_dwordx4 v[216:217], off
	v_lshl_add_u64 v[216:217], v[220:221], 0, s[10:11]
	s_mov_b32 m0, s43
	s_nop 0
	global_load_lds_dwordx4 v[216:217], off
	v_lshl_add_u64 v[216:217], v[222:223], 0, s[10:11]
	s_mov_b32 m0, s44
	s_nop 0
	global_load_lds_dwordx4 v[216:217], off
	s_waitcnt vmcnt(8)
	s_waitcnt lgkmcnt(0)
	s_barrier
	s_waitcnt lgkmcnt(0)
	v_mfma_f32_16x16x32_bf16 v[60:63], v[128:131], v[160:163], v[60:63]
	v_mfma_f32_16x16x32_bf16 v[56:59], v[136:139], v[160:163], v[56:59]
	v_mfma_f32_16x16x32_bf16 v[44:47], v[128:131], v[168:171], v[44:47]
	v_mfma_f32_16x16x32_bf16 v[40:43], v[136:139], v[168:171], v[40:43]
	v_mfma_f32_16x16x32_bf16 v[28:31], v[128:131], v[192:195], v[28:31]
	v_mfma_f32_16x16x32_bf16 v[24:27], v[136:139], v[192:195], v[24:27]
	v_mfma_f32_16x16x32_bf16 v[12:15], v[128:131], v[200:203], v[12:15]
	v_mfma_f32_16x16x32_bf16 v[8:11], v[136:139], v[200:203], v[8:11]
	v_mfma_f32_16x16x32_bf16 v[60:63], v[132:135], v[164:167], v[60:63]
	v_mfma_f32_16x16x32_bf16 v[56:59], v[140:143], v[164:167], v[56:59]
	v_mfma_f32_16x16x32_bf16 v[44:47], v[132:135], v[172:175], v[44:47]
	v_mfma_f32_16x16x32_bf16 v[40:43], v[140:143], v[172:175], v[40:43]
	v_mfma_f32_16x16x32_bf16 v[28:31], v[132:135], v[196:199], v[28:31]
	v_mfma_f32_16x16x32_bf16 v[24:27], v[140:143], v[196:199], v[24:27]
	v_mfma_f32_16x16x32_bf16 v[12:15], v[132:135], v[212:215], v[12:15]
	v_mfma_f32_16x16x32_bf16 v[8:11], v[140:143], v[212:215], v[8:11]
	v_mfma_f32_16x16x32_bf16 v[52:55], v[144:147], v[160:163], v[52:55]
	v_mfma_f32_16x16x32_bf16 v[48:51], v[152:155], v[160:163], v[48:51]
	v_mfma_f32_16x16x32_bf16 v[36:39], v[144:147], v[168:171], v[36:39]
	v_mfma_f32_16x16x32_bf16 v[32:35], v[152:155], v[168:171], v[32:35]
	v_mfma_f32_16x16x32_bf16 v[20:23], v[144:147], v[192:195], v[20:23]
	v_mfma_f32_16x16x32_bf16 v[16:19], v[152:155], v[192:195], v[16:19]
	v_mfma_f32_16x16x32_bf16 v[4:7], v[144:147], v[200:203], v[4:7]
	v_mfma_f32_16x16x32_bf16 v[0:3], v[152:155], v[200:203], v[0:3]
	v_mfma_f32_16x16x32_bf16 v[52:55], v[148:151], v[164:167], v[52:55]
	v_mfma_f32_16x16x32_bf16 v[48:51], v[156:159], v[164:167], v[48:51]
	v_mfma_f32_16x16x32_bf16 v[36:39], v[148:151], v[172:175], v[36:39]
	v_mfma_f32_16x16x32_bf16 v[32:35], v[156:159], v[172:175], v[32:35]
	v_mfma_f32_16x16x32_bf16 v[20:23], v[148:151], v[196:199], v[20:23]
	v_mfma_f32_16x16x32_bf16 v[16:19], v[156:159], v[196:199], v[16:19]
	v_mfma_f32_16x16x32_bf16 v[4:7], v[148:151], v[212:215], v[4:7]
	v_mfma_f32_16x16x32_bf16 v[0:3], v[156:159], v[212:215], v[0:3]
	s_barrier
	s_add_i32 s53, s53, 2
	s_add_u32 s6, s6, 0x100
	s_addc_u32 s7, s7, 0
	s_add_u32 s51, s51, 0x100
	s_addc_u32 s52, s52, 0
	s_cmp_gt_u32 s53, 13
	s_cbranch_scc0 .LBB0_469
	s_and_b64 vcc, exec, s[12:13]
	s_cbranch_vccz .LBB0_472
	s_barrier

; #define PG8_STAGE(bufoff, gbase, voff) do { _Pragma("unroll") for (int _i = 0; _i < 2; ++_i) \
;         __builtin_amdgcn_global_load_lds((const unsigned*)((const char*)(gbase) + (voff)[_i]), (PG8_LAS unsigned*)(lds + (bufoff) + ldsw + _i * 8192), 16, 0, 0); } while (0)
; #define PG8_LDA(dst, b, h) do { _Pragma("unroll") for (int m = 0; m < 4; ++m) _Pragma("unroll") for (int k = 0; k < 2; ++k) dst[m][k] = *(const PG8_LAS bf16x8*)(lds + PG8_SA(b, h) + aoff + m * 2048 + k * 1024); } while (0)
; #define PG8_LDB(dst, b, h) do { _Pragma("unroll") for (int n = 0; n < 2; ++n) _Pragma("unroll") for (int k = 0; k < 2; ++k) dst[n][k] = *(const PG8_LAS bf16x8*)(lds + PG8_SB(b, h) + boff + n * 2048 + k * 1024); } while (0)
; #define PG8_MMA(ai, bj, At, Bt) do { __builtin_amdgcn_s_setprio(1); _Pragma("unroll") for (int m = 0; m < 4; ++m) _Pragma("unroll") for (int n = 0; n < 2; ++n) _Pragma("unroll") for (int k = 0; k < 2; ++k) \
;         acc[ai][bj][m][n] = __builtin_amdgcn_mfma_f32_16x16x32_bf16(Bt[n][k], At[m][k], acc[ai][bj][m][n], 0, 0, 0); __builtin_amdgcn_s_setprio(0); } while (0)
; #define PG8_WAIT_V(n) asm volatile("s_waitcnt vmcnt(" #n ")" ::: "memory")
; #define PG8_WAIT_L(n) asm volatile("s_waitcnt lgkmcnt(" #n ")" ::: "memory")
; #define PG8_BAR __builtin_amdgcn_s_barrier()
; #define PG8_SCHED __builtin_amdgcn_sched_barrier(0)
; template <class Epi, class Sched, bool ALIGN_EPI = false, bool SP2 = false>
; __device__ __forceinline__ void gemm_phase(PG8_LAS unsigned char* lds, const Gemm g, const Sched& S, const Epi& E, const int wave_s) {
;     ...
;             PG8_LDB(B0, 0, 0); PG8_LDB(B1, 0, 1); PG8_SCHED; PG8_LDA(At, 0, 0); PG8_STAGE(PG8_SA(1, 1), a1 + hstep, voffA);
;             PG8_WAIT_V(8); PG8_WAIT_L(0); PG8_BAR; PG8_MMA(0, 0, At, B0); PG8_MMA(0, 1, At, B1); PG8_BAR; PG8_SCHED;
;             PG8_LDA(At, 0, 1); PG8_STAGE(PG8_SB(0, 0), b2, voffB); PG8_STAGE(PG8_SB(0, 1), b2 + hstep, voffB); PG8_STAGE(PG8_SA(0, 0), a2, voffA);
.LBB0_565:
	ds_read_b128 v[0:3], v239
	ds_read_b128 v[4:7], v239 offset:1024
	ds_read_b128 v[32:35], v239 offset:2048
	ds_read_b128 v[36:39], v239 offset:3072
	ds_read_b128 v[158:161], v240
	ds_read_b128 v[162:165], v240 offset:1024
	ds_read_b128 v[166:169], v240 offset:2048
	ds_read_b128 v[170:173], v240 offset:3072
	s_add_u32 s4, s0, 0xfffc0080
	s_addc_u32 s5, s1, -1
	s_cmp_eq_u32 s16, 12
	s_cselect_b32 s9, s95, s5
	s_cselect_b32 s8, s94, s4
	s_cselect_b32 s7, s11, s15
	s_cselect_b32 s6, s13, s14
	v_lshl_add_u64 v[206:207], s[0:1], 0, v[154:155]
	s_add_i32 m0, s2, 0xc000
	ds_read_b128 v[174:177], v241
	ds_read_b128 v[178:181], v241 offset:1024
	ds_read_b128 v[182:185], v241 offset:2048
	ds_read_b128 v[186:189], v241 offset:3072
	ds_read_b128 v[190:193], v241 offset:4096
	ds_read_b128 v[194:197], v241 offset:5120
	ds_read_b128 v[198:201], v241 offset:6144
	ds_read_b128 v[202:205], v241 offset:7168
	global_load_lds_dwordx4 v[206:207], off
	v_lshl_add_u64 v[206:207], s[0:1], 0, v[156:157]
	s_add_i32 m0, s2, 0xe000
	s_nop 0
	global_load_lds_dwordx4 v[206:207], off
	s_waitcnt vmcnt(8)
	s_waitcnt lgkmcnt(0)
	s_barrier
	s_waitcnt lgkmcnt(0)
	v_mfma_f32_16x16x32_bf16 v[140:143], v[0:3], v[174:177], v[140:143]
	v_mfma_f32_16x16x32_bf16 v[136:139], v[32:35], v[174:177], v[136:139]
	v_mfma_f32_16x16x32_bf16 v[124:127], v[0:3], v[182:185], v[124:127]
	v_mfma_f32_16x16x32_bf16 v[120:123], v[32:35], v[182:185], v[120:123]
	v_mfma_f32_16x16x32_bf16 v[52:55], v[0:3], v[190:193], v[52:55]
	v_mfma_f32_16x16x32_bf16 v[48:51], v[32:35], v[190:193], v[48:51]
	v_mfma_f32_16x16x32_bf16 v[44:47], v[0:3], v[198:201], v[44:47]
	v_mfma_f32_16x16x32_bf16 v[40:43], v[32:35], v[198:201], v[40:43]
	v_mfma_f32_16x16x32_bf16 v[140:143], v[4:7], v[178:181], v[140:143]
	v_mfma_f32_16x16x32_bf16 v[136:139], v[36:39], v[178:181], v[136:139]
	v_mfma_f32_16x16x32_bf16 v[124:127], v[4:7], v[186:189], v[124:127]
	v_mfma_f32_16x16x32_bf16 v[120:123], v[36:39], v[186:189], v[120:123]
	v_mfma_f32_16x16x32_bf16 v[52:55], v[4:7], v[194:197], v[52:55]
	v_mfma_f32_16x16x32_bf16 v[48:51], v[36:39], v[194:197], v[48:51]
	v_mfma_f32_16x16x32_bf16 v[44:47], v[4:7], v[202:205], v[44:47]
	v_mfma_f32_16x16x32_bf16 v[40:43], v[36:39], v[202:205], v[40:43]
	v_mfma_f32_16x16x32_bf16 v[132:135], v[158:161], v[174:177], v[132:135]
	v_mfma_f32_16x16x32_bf16 v[128:131], v[166:169], v[174:177], v[128:131]
	v_mfma_f32_16x16x32_bf16 v[116:119], v[158:161], v[182:185], v[116:119]
	v_mfma_f32_16x16x32_bf16 v[112:115], v[166:169], v[182:185], v[112:115]
	v_mfma_f32_16x16x32_bf16 v[20:23], v[158:161], v[190:193], v[20:23]
	v_mfma_f32_16x16x32_bf16 v[16:19], v[166:169], v[190:193], v[16:19]
	v_mfma_f32_16x16x32_bf16 v[12:15], v[158:161], v[198:201], v[12:15]
	v_mfma_f32_16x16x32_bf16 v[8:11], v[166:169], v[198:201], v[8:11]
	v_mfma_f32_16x16x32_bf16 v[132:135], v[162:165], v[178:181], v[132:135]
	v_mfma_f32_16x16x32_bf16 v[128:131], v[170:173], v[178:181], v[128:131]
	v_mfma_f32_16x16x32_bf16 v[116:119], v[162:165], v[186:189], v[116:119]
	v_mfma_f32_16x16x32_bf16 v[112:115], v[170:173], v[186:189], v[112:115]
	v_mfma_f32_16x16x32_bf16 v[20:23], v[162:165], v[194:197], v[20:23]
	v_mfma_f32_16x16x32_bf16 v[16:19], v[170:173], v[194:197], v[16:19]
	v_mfma_f32_16x16x32_bf16 v[12:15], v[162:165], v[202:205], v[12:15]
	v_mfma_f32_16x16x32_bf16 v[8:11], v[170:173], v[202:205], v[8:11]
	s_barrier
	s_add_i32 s4, s75, s33
	v_lshl_add_u64 v[206:207], s[6:7], 0, v[146:147]
	s_mov_b32 m0, s4
	ds_read_b128 v[174:177], v241 offset:16384
	ds_read_b128 v[178:181], v241 offset:17408
	ds_read_b128 v[182:185], v241 offset:18432
	ds_read_b128 v[186:189], v241 offset:19456
	ds_read_b128 v[190:193], v241 offset:20480
	ds_read_b128 v[194:197], v241 offset:21504
	ds_read_b128 v[198:201], v241 offset:22528
	ds_read_b128 v[202:205], v241 offset:23552
	global_load_lds_dwordx4 v[206:207], off
	s_add_i32 m0, s4, 0x2000
	s_add_u32 s18, s6, 0x40000
	v_lshl_add_u64 v[208:209], s[6:7], 0, v[150:151]
	s_addc_u32 s19, s7, 0
	s_add_i32 s4, s73, s33
	global_load_lds_dwordx4 v[208:209], off
	v_lshl_add_u64 v[210:211], s[18:19], 0, v[146:147]
	s_mov_b32 m0, s4
	v_lshl_add_u64 v[212:213], s[8:9], 0, v[148:149]
	global_load_lds_dwordx4 v[210:211], off
	v_lshl_add_u64 v[210:211], s[18:19], 0, v[150:151]
	s_add_i32 m0, s4, 0x2000
	s_nop 0
	global_load_lds_dwordx4 v[210:211], off
	v_lshl_add_u64 v[210:211], s[8:9], 0, v[144:145]
	s_mov_b32 m0, s2
	s_nop 0
	global_load_lds_dwordx4 v[210:211], off
	s_mov_b32 m0, s3
	s_nop 0
	global_load_lds_dwordx4 v[212:213], off
	s_waitcnt vmcnt(8)
	s_waitcnt lgkmcnt(0)
	s_barrier
; #define PG8_STAGE(bufoff, gbase, voff) do { _Pragma("unroll") for (int _i = 0; _i < 2; ++_i) \
;         __builtin_amdgcn_global_load_lds((const unsigned*)((const char*)(gbase) + (voff)[_i]), (PG8_LAS unsigned*)(lds + (bufoff) + ldsw + _i * 8192), 16, 0, 0); } while (0)
; #define PG8_LDA(dst, b, h) do { _Pragma("unroll") for (int m = 0; m < 4; ++m) _Pragma("unroll") for (int k = 0; k < 2; ++k) dst[m][k] = *(const PG8_LAS bf16x8*)(lds + PG8_SA(b, h) + aoff + m * 2048 + k * 1024); } while (0)
; #define PG8_LDB(dst, b, h) do { _Pragma("unroll") for (int n = 0; n < 2; ++n) _Pragma("unroll") for (int k = 0; k < 2; ++k) dst[n][k] = *(const PG8_LAS bf16x8*)(lds + PG8_SB(b, h) + boff + n * 2048 + k * 1024); } while (0)
; #define PG8_MMA(ai, bj, At, Bt) do { __builtin_amdgcn_s_setprio(1); _Pragma("unroll") for (int m = 0; m < 4; ++m) _Pragma("unroll") for (int n = 0; n < 2; ++n) _Pragma("unroll") for (int k = 0; k < 2; ++k) \
;         acc[ai][bj][m][n] = __builtin_amdgcn_mfma_f32_16x16x32_bf16(Bt[n][k], At[m][k], acc[ai][bj][m][n], 0, 0, 0); __builtin_amdgcn_s_setprio(0); } while (0)
; #define PG8_WAIT_V(n) asm volatile("s_waitcnt vmcnt(" #n ")" ::: "memory")
; #define PG8_WAIT_L(n) asm volatile("s_waitcnt lgkmcnt(" #n ")" ::: "memory")
; #define PG8_BAR __builtin_amdgcn_s_barrier()
; #define PG8_SCHED __builtin_amdgcn_sched_barrier(0)
; template <class Epi, class Sched, bool ALIGN_EPI = false, bool SP2 = false>
; __device__ __forceinline__ void gemm_phase(PG8_LAS unsigned char* lds, const Gemm g, const Sched& S, const Epi& E, const int wave_s) {
;     ...
;             PG8_WAIT_V(8); PG8_WAIT_L(0); PG8_BAR; PG8_MMA(1, 0, At, B0); PG8_MMA(1, 1, At, B1); PG8_BAR; PG8_SCHED;
;             PG8_LDB(B0, 1, 0); PG8_LDB(B1, 1, 1); PG8_SCHED; PG8_LDA(At, 1, 0); PG8_STAGE(PG8_SA(0, 1), a2 + hstep, voffA);
;             PG8_WAIT_V(8); PG8_WAIT_L(0); PG8_BAR; PG8_MMA(0, 0, At, B0); PG8_MMA(0, 1, At, B1); PG8_BAR; PG8_SCHED;
	s_waitcnt lgkmcnt(0)
	v_mfma_f32_16x16x32_bf16 v[108:111], v[0:3], v[174:177], v[108:111]
	v_mfma_f32_16x16x32_bf16 v[104:107], v[32:35], v[174:177], v[104:107]
	v_mfma_f32_16x16x32_bf16 v[92:95], v[0:3], v[182:185], v[92:95]
	v_mfma_f32_16x16x32_bf16 v[88:91], v[32:35], v[182:185], v[88:91]
	v_mfma_f32_16x16x32_bf16 v[60:63], v[0:3], v[190:193], v[60:63]
	v_mfma_f32_16x16x32_bf16 v[56:59], v[32:35], v[190:193], v[56:59]
	v_mfma_f32_16x16x32_bf16 v[0:3], v[0:3], v[198:201], v[76:79]
	v_mfma_f32_16x16x32_bf16 v[108:111], v[4:7], v[178:181], v[108:111]
	v_mfma_f32_16x16x32_bf16 v[104:107], v[36:39], v[178:181], v[104:107]
	v_mfma_f32_16x16x32_bf16 v[92:95], v[4:7], v[186:189], v[92:95]
	v_mfma_f32_16x16x32_bf16 v[88:91], v[36:39], v[186:189], v[88:91]
	v_mfma_f32_16x16x32_bf16 v[60:63], v[4:7], v[194:197], v[60:63]
	v_mfma_f32_16x16x32_bf16 v[56:59], v[36:39], v[194:197], v[56:59]
	v_mfma_f32_16x16x32_bf16 v[0:3], v[4:7], v[202:205], v[0:3]
	v_mfma_f32_16x16x32_bf16 v[4:7], v[32:35], v[198:201], v[72:75]
	v_mfma_f32_16x16x32_bf16 v[4:7], v[36:39], v[202:205], v[4:7]
	v_mfma_f32_16x16x32_bf16 v[72:75], v[158:161], v[182:185], v[84:87]
	v_mfma_f32_16x16x32_bf16 v[84:87], v[162:165], v[186:189], v[72:75]
	v_mfma_f32_16x16x32_bf16 v[72:75], v[166:169], v[182:185], v[80:83]
	v_mfma_f32_16x16x32_bf16 v[28:31], v[158:161], v[190:193], v[28:31]
	v_mfma_f32_16x16x32_bf16 v[24:27], v[166:169], v[190:193], v[24:27]
	v_mfma_f32_16x16x32_bf16 v[68:71], v[158:161], v[198:201], v[68:71]
	v_mfma_f32_16x16x32_bf16 v[64:67], v[166:169], v[198:201], v[64:67]
	v_mfma_f32_16x16x32_bf16 v[32:35], v[158:161], v[174:177], v[100:103]
	v_mfma_f32_16x16x32_bf16 v[36:39], v[166:169], v[174:177], v[96:99]
	v_mfma_f32_16x16x32_bf16 v[80:83], v[170:173], v[186:189], v[72:75]
	v_mfma_f32_16x16x32_bf16 v[28:31], v[162:165], v[194:197], v[28:31]
	v_mfma_f32_16x16x32_bf16 v[24:27], v[170:173], v[194:197], v[24:27]
	v_mfma_f32_16x16x32_bf16 v[68:71], v[162:165], v[202:205], v[68:71]
	v_mfma_f32_16x16x32_bf16 v[64:67], v[170:173], v[202:205], v[64:67]
	v_mfma_f32_16x16x32_bf16 v[32:35], v[162:165], v[178:181], v[32:35]
	v_mfma_f32_16x16x32_bf16 v[36:39], v[170:173], v[178:181], v[36:39]
	s_barrier
	s_add_i32 s4, 0, 0x18000
	s_add_i32 s5, 0, 0x1c000
	v_add_u32_e32 v100, s4, v238
	v_add_u32_e32 v152, s5, v238
	ds_read_b128 v[72:75], v100
	ds_read_b128 v[76:79], v100 offset:1024
	ds_read_b128 v[96:99], v100 offset:2048
	ds_read_b128 v[100:103], v100 offset:3072
	ds_read_b128 v[158:161], v152
	ds_read_b128 v[162:165], v152 offset:1024
	ds_read_b128 v[166:169], v152 offset:2048
	ds_read_b128 v[170:173], v152 offset:3072
	s_add_u32 s8, s8, 0x40000
	s_addc_u32 s9, s9, 0
	s_mov_b32 m0, s76
	v_lshl_add_u64 v[214:215], s[8:9], 0, v[144:145]
	ds_read_b128 v[174:177], v241 offset:32768
	ds_read_b128 v[178:181], v241 offset:33792
	ds_read_b128 v[182:185], v241 offset:34816
	ds_read_b128 v[186:189], v241 offset:35840
	ds_read_b128 v[190:193], v241 offset:36864
	ds_read_b128 v[194:197], v241 offset:37888
	ds_read_b128 v[198:201], v241 offset:38912
	ds_read_b128 v[202:205], v241 offset:39936
	global_load_lds_dwordx4 v[214:215], off
	v_lshl_add_u64 v[214:215], s[8:9], 0, v[148:149]
	s_mov_b32 m0, s77
	s_nop 0
	global_load_lds_dwordx4 v[214:215], off
	s_waitcnt vmcnt(8)
	s_waitcnt lgkmcnt(0)
	s_barrier
	s_waitcnt lgkmcnt(0)
	v_mfma_f32_16x16x32_bf16 v[140:143], v[72:75], v[174:177], v[140:143]
	v_mfma_f32_16x16x32_bf16 v[136:139], v[96:99], v[174:177], v[136:139]
	v_mfma_f32_16x16x32_bf16 v[124:127], v[72:75], v[182:185], v[124:127]
	v_mfma_f32_16x16x32_bf16 v[120:123], v[96:99], v[182:185], v[120:123]
	v_mfma_f32_16x16x32_bf16 v[52:55], v[72:75], v[190:193], v[52:55]
	v_mfma_f32_16x16x32_bf16 v[48:51], v[96:99], v[190:193], v[48:51]
	v_mfma_f32_16x16x32_bf16 v[44:47], v[72:75], v[198:201], v[44:47]
	v_mfma_f32_16x16x32_bf16 v[40:43], v[96:99], v[198:201], v[40:43]
	v_mfma_f32_16x16x32_bf16 v[140:143], v[76:79], v[178:181], v[140:143]
	v_mfma_f32_16x16x32_bf16 v[136:139], v[100:103], v[178:181], v[136:139]
	v_mfma_f32_16x16x32_bf16 v[124:127], v[76:79], v[186:189], v[124:127]
	v_mfma_f32_16x16x32_bf16 v[120:123], v[100:103], v[186:189], v[120:123]
	v_mfma_f32_16x16x32_bf16 v[52:55], v[76:79], v[194:197], v[52:55]
	v_mfma_f32_16x16x32_bf16 v[48:51], v[100:103], v[194:197], v[48:51]
	v_mfma_f32_16x16x32_bf16 v[44:47], v[76:79], v[202:205], v[44:47]
	v_mfma_f32_16x16x32_bf16 v[40:43], v[100:103], v[202:205], v[40:43]
	v_mfma_f32_16x16x32_bf16 v[132:135], v[158:161], v[174:177], v[132:135]
	v_mfma_f32_16x16x32_bf16 v[128:131], v[166:169], v[174:177], v[128:131]
	v_mfma_f32_16x16x32_bf16 v[116:119], v[158:161], v[182:185], v[116:119]
	v_mfma_f32_16x16x32_bf16 v[112:115], v[166:169], v[182:185], v[112:115]
	v_mfma_f32_16x16x32_bf16 v[20:23], v[158:161], v[190:193], v[20:23]
	v_mfma_f32_16x16x32_bf16 v[16:19], v[166:169], v[190:193], v[16:19]
	v_mfma_f32_16x16x32_bf16 v[12:15], v[158:161], v[198:201], v[12:15]
	v_mfma_f32_16x16x32_bf16 v[8:11], v[166:169], v[198:201], v[8:11]
	v_mfma_f32_16x16x32_bf16 v[132:135], v[162:165], v[178:181], v[132:135]
	v_mfma_f32_16x16x32_bf16 v[128:131], v[170:173], v[178:181], v[128:131]
	v_mfma_f32_16x16x32_bf16 v[116:119], v[162:165], v[186:189], v[116:119]
	v_mfma_f32_16x16x32_bf16 v[112:115], v[170:173], v[186:189], v[112:115]
	v_mfma_f32_16x16x32_bf16 v[20:23], v[162:165], v[194:197], v[20:23]
	v_mfma_f32_16x16x32_bf16 v[16:19], v[170:173], v[194:197], v[16:19]
	v_mfma_f32_16x16x32_bf16 v[12:15], v[162:165], v[202:205], v[12:15]
	v_mfma_f32_16x16x32_bf16 v[8:11], v[170:173], v[202:205], v[8:11]
	s_barrier
; #define PG8_STAGE(bufoff, gbase, voff) do { _Pragma("unroll") for (int _i = 0; _i < 2; ++_i) \
;         __builtin_amdgcn_global_load_lds((const unsigned*)((const char*)(gbase) + (voff)[_i]), (PG8_LAS unsigned*)(lds + (bufoff) + ldsw + _i * 8192), 16, 0, 0); } while (0)
; #define PG8_LDA(dst, b, h) do { _Pragma("unroll") for (int m = 0; m < 4; ++m) _Pragma("unroll") for (int k = 0; k < 2; ++k) dst[m][k] = *(const PG8_LAS bf16x8*)(lds + PG8_SA(b, h) + aoff + m * 2048 + k * 1024); } while (0)
; #define PG8_MMA(ai, bj, At, Bt) do { __builtin_amdgcn_s_setprio(1); _Pragma("unroll") for (int m = 0; m < 4; ++m) _Pragma("unroll") for (int n = 0; n < 2; ++n) _Pragma("unroll") for (int k = 0; k < 2; ++k) \
;         acc[ai][bj][m][n] = __builtin_amdgcn_mfma_f32_16x16x32_bf16(Bt[n][k], At[m][k], acc[ai][bj][m][n], 0, 0, 0); __builtin_amdgcn_s_setprio(0); } while (0)
; #define PG8_WAIT_V(n) asm volatile("s_waitcnt vmcnt(" #n ")" ::: "memory")
; #define PG8_WAIT_L(n) asm volatile("s_waitcnt lgkmcnt(" #n ")" ::: "memory")
; #define PG8_BAR __builtin_amdgcn_s_barrier()
; #define PG8_SCHED __builtin_amdgcn_sched_barrier(0)
; template <class Epi, class Sched, bool ALIGN_EPI = false, bool SP2 = false>
; __device__ __forceinline__ void gemm_phase(PG8_LAS unsigned char* lds, const Gemm g, const Sched& S, const Epi& E, const int wave_s) {
;     ...
;             PG8_LDA(At, 1, 1); PG8_STAGE(PG8_SB(1, 0), b3, voffB); PG8_STAGE(PG8_SB(1, 1), b3 + hstep, voffB); PG8_STAGE(PG8_SA(1, 0), a3, voffA);
;             PG8_WAIT_V(8); PG8_WAIT_L(0); PG8_BAR; PG8_MMA(1, 0, At, B0); PG8_MMA(1, 1, At, B1); PG8_BAR; PG8_SCHED;
	s_add_i32 s4, s4, s33
	v_lshl_add_u64 v[206:207], v[206:207], 0, s[64:65]
	s_mov_b32 m0, s4
	ds_read_b128 v[174:177], v241 offset:49152
	ds_read_b128 v[178:181], v241 offset:50176
	ds_read_b128 v[182:185], v241 offset:51200
	ds_read_b128 v[186:189], v241 offset:52224
	ds_read_b128 v[190:193], v241 offset:53248
	ds_read_b128 v[194:197], v241 offset:54272
	ds_read_b128 v[198:201], v241 offset:55296
	ds_read_b128 v[202:205], v241 offset:56320
	global_load_lds_dwordx4 v[206:207], off
	s_add_i32 m0, s4, 0x2000
	s_add_u32 s6, s6, 0x40080
	v_lshl_add_u64 v[206:207], v[208:209], 0, s[64:65]
	s_addc_u32 s7, s7, 0
	s_add_i32 s4, s5, s33
	global_load_lds_dwordx4 v[206:207], off
	v_lshl_add_u64 v[206:207], s[6:7], 0, v[146:147]
	s_mov_b32 m0, s4
	s_nop 0
	global_load_lds_dwordx4 v[206:207], off
	v_lshl_add_u64 v[206:207], s[6:7], 0, v[150:151]
	s_add_i32 m0, s4, 0x2000
	s_nop 0
	global_load_lds_dwordx4 v[206:207], off
	v_lshl_add_u64 v[206:207], v[210:211], 0, s[64:65]
	s_mov_b32 m0, s87
	s_nop 0
	global_load_lds_dwordx4 v[206:207], off
	v_lshl_add_u64 v[206:207], v[212:213], 0, s[64:65]
	s_mov_b32 m0, s72
	s_nop 0
	global_load_lds_dwordx4 v[206:207], off
	s_waitcnt vmcnt(8)
	s_waitcnt lgkmcnt(0)
	s_barrier
	s_waitcnt lgkmcnt(0)
	v_mfma_f32_16x16x32_bf16 v[108:111], v[72:75], v[174:177], v[108:111]
	v_mfma_f32_16x16x32_bf16 v[92:95], v[72:75], v[182:185], v[92:95]
	v_mfma_f32_16x16x32_bf16 v[60:63], v[72:75], v[190:193], v[60:63]
	v_mfma_f32_16x16x32_bf16 v[0:3], v[72:75], v[198:201], v[0:3]
	v_mfma_f32_16x16x32_bf16 v[108:111], v[76:79], v[178:181], v[108:111]
	v_mfma_f32_16x16x32_bf16 v[104:107], v[96:99], v[174:177], v[104:107]
	v_mfma_f32_16x16x32_bf16 v[92:95], v[76:79], v[186:189], v[92:95]
	v_mfma_f32_16x16x32_bf16 v[88:91], v[96:99], v[182:185], v[88:91]
	v_mfma_f32_16x16x32_bf16 v[60:63], v[76:79], v[194:197], v[60:63]
	v_mfma_f32_16x16x32_bf16 v[56:59], v[96:99], v[190:193], v[56:59]
	v_mfma_f32_16x16x32_bf16 v[76:79], v[76:79], v[202:205], v[0:3]
	v_mfma_f32_16x16x32_bf16 v[0:3], v[96:99], v[198:201], v[4:7]
	v_mfma_f32_16x16x32_bf16 v[104:107], v[100:103], v[178:181], v[104:107]
	v_mfma_f32_16x16x32_bf16 v[88:91], v[100:103], v[186:189], v[88:91]
	v_mfma_f32_16x16x32_bf16 v[56:59], v[100:103], v[194:197], v[56:59]
	v_mfma_f32_16x16x32_bf16 v[72:75], v[100:103], v[202:205], v[0:3]
	v_mfma_f32_16x16x32_bf16 v[0:3], v[158:161], v[174:177], v[32:35]
	v_mfma_f32_16x16x32_bf16 v[100:103], v[162:165], v[178:181], v[0:3]
	v_mfma_f32_16x16x32_bf16 v[0:3], v[166:169], v[174:177], v[36:39]
	v_mfma_f32_16x16x32_bf16 v[96:99], v[170:173], v[178:181], v[0:3]
	v_mfma_f32_16x16x32_bf16 v[0:3], v[158:161], v[182:185], v[84:87]
	v_mfma_f32_16x16x32_bf16 v[84:87], v[162:165], v[186:189], v[0:3]
	v_mfma_f32_16x16x32_bf16 v[0:3], v[166:169], v[182:185], v[80:83]
	v_mfma_f32_16x16x32_bf16 v[80:83], v[170:173], v[186:189], v[0:3]
	v_mfma_f32_16x16x32_bf16 v[0:3], v[158:161], v[190:193], v[28:31]
	v_mfma_f32_16x16x32_bf16 v[28:31], v[162:165], v[194:197], v[0:3]
	v_mfma_f32_16x16x32_bf16 v[0:3], v[166:169], v[190:193], v[24:27]
	v_mfma_f32_16x16x32_bf16 v[24:27], v[170:173], v[194:197], v[0:3]
	v_mfma_f32_16x16x32_bf16 v[0:3], v[158:161], v[198:201], v[68:71]
	v_mfma_f32_16x16x32_bf16 v[68:71], v[162:165], v[202:205], v[0:3]
	v_mfma_f32_16x16x32_bf16 v[0:3], v[166:169], v[198:201], v[64:67]
	v_mfma_f32_16x16x32_bf16 v[64:67], v[170:173], v[202:205], v[0:3]
	s_barrier
	s_add_i32 s16, s16, 2
	s_add_u32 s0, s0, 0x100
	s_addc_u32 s1, s1, 0
	s_add_u32 s14, s14, 0x100
	s_addc_u32 s15, s15, 0
	s_cmp_gt_u32 s16, 13
	s_cbranch_scc0 .LBB0_565
	s_mul_i32 s36, s12, 0xfe
	s_add_i32 s4, s36, -1
	v_add_u32_e32 v224, s48, v236
	v_add_u32_e32 v224, s4, v224
	v_ashrrev_i32_e32 v225, 31, v224
	v_lshl_add_u64 v[226:227], v[224:225], 2, s[60:61]
	global_load_dword v248, v[226:227], off
	global_load_dword v249, v[226:227], off offset:64
	global_load_dword v250, v[226:227], off offset:128
	global_load_dword v251, v[226:227], off offset:192
	global_load_dword v252, v[226:227], off offset:512
	global_load_dword v253, v[226:227], off offset:576
	global_load_dword v229, v[226:227], off offset:640
	global_load_dword v230, v[226:227], off offset:704
	s_and_b64 vcc, exec, s[80:81]
	s_cbranch_vccz .LBB0_568
	s_barrier

; #define PG8_STAGE(bufoff, gbase, voff) do { _Pragma("unroll") for (int _i = 0; _i < 2; ++_i) \
;         __builtin_amdgcn_global_load_lds((const unsigned*)((const char*)(gbase) + (voff)[_i]), (PG8_LAS unsigned*)(lds + (bufoff) + ldsw + _i * 8192), 16, 0, 0); } while (0)
; #define PG8_LDA(dst, b, h) do { _Pragma("unroll") for (int m = 0; m < 4; ++m) _Pragma("unroll") for (int k = 0; k < 2; ++k) dst[m][k] = *(const PG8_LAS bf16x8*)(lds + PG8_SA(b, h) + aoff + m * 2048 + k * 1024); } while (0)
; #define PG8_LDB(dst, b, h) do { _Pragma("unroll") for (int n = 0; n < 2; ++n) _Pragma("unroll") for (int k = 0; k < 2; ++k) dst[n][k] = *(const PG8_LAS bf16x8*)(lds + PG8_SB(b, h) + boff + n * 2048 + k * 1024); } while (0)
; #define PG8_MMA(ai, bj, At, Bt) do { __builtin_amdgcn_s_setprio(1); _Pragma("unroll") for (int m = 0; m < 4; ++m) _Pragma("unroll") for (int n = 0; n < 2; ++n) _Pragma("unroll") for (int k = 0; k < 2; ++k) \
;         acc[ai][bj][m][n] = __builtin_amdgcn_mfma_f32_16x16x32_bf16(Bt[n][k], At[m][k], acc[ai][bj][m][n], 0, 0, 0); __builtin_amdgcn_s_setprio(0); } while (0)
; #define PG8_WAIT_V(n) asm volatile("s_waitcnt vmcnt(" #n ")" ::: "memory")
; #define PG8_WAIT_L(n) asm volatile("s_waitcnt lgkmcnt(" #n ")" ::: "memory")
; #define PG8_BAR __builtin_amdgcn_s_barrier()
; #define PG8_SCHED __builtin_amdgcn_sched_barrier(0)
; template <class Epi, class Sched, bool ALIGN_EPI = false, bool SP2 = false>
; __device__ __forceinline__ void gemm_phase(PG8_LAS unsigned char* lds, const Gemm g, const Sched& S, const Epi& E, const int wave_s) {
;     ...
;             PG8_LDB(B0, 0, 0); PG8_LDB(B1, 0, 1); PG8_SCHED; PG8_LDA(At, 0, 0); PG8_STAGE(PG8_SA(1, 1), a1 + hstep, voffA);
;             PG8_WAIT_V(8); PG8_WAIT_L(0); PG8_BAR; PG8_MMA(0, 0, At, B0); PG8_MMA(0, 1, At, B1); PG8_BAR; PG8_SCHED;
;             PG8_LDA(At, 0, 1); PG8_STAGE(PG8_SB(0, 0), b2, voffB); PG8_STAGE(PG8_SB(0, 1), b2 + hstep, voffB); PG8_STAGE(PG8_SA(0, 0), a2, voffA);
.LBB0_838:
	ds_read_b128 v[128:131], v189
	ds_read_b128 v[132:135], v189 offset:1024
	ds_read_b128 v[136:139], v189 offset:2048
	ds_read_b128 v[140:143], v189 offset:3072
	ds_read_b128 v[144:147], v190
	ds_read_b128 v[148:151], v190 offset:1024
	ds_read_b128 v[152:155], v190 offset:2048
	ds_read_b128 v[156:159], v190 offset:3072
	s_add_u32 s14, s2, 0x100
	s_addc_u32 s15, s3, 0
	s_cmp_eq_u32 s58, 40
	s_cselect_b32 s19, s5, s15
	s_cselect_b32 s18, s4, s14
	s_cselect_b32 s17, s13, s55
	s_cselect_b32 s16, s12, s54
	v_lshl_add_u64 v[184:185], s[2:3], 0, v[176:177]
	s_add_i32 m0, s24, 0xc000
	ds_read_b128 v[160:163], v191
	ds_read_b128 v[164:167], v191 offset:1024
	ds_read_b128 v[192:195], v191 offset:2048
	ds_read_b128 v[196:199], v191 offset:3072
	ds_read_b128 v[200:203], v191 offset:4096
	ds_read_b128 v[204:207], v191 offset:5120
	ds_read_b128 v[208:211], v191 offset:6144
	ds_read_b128 v[212:215], v191 offset:7168
	global_load_lds_dwordx4 v[184:185], off
	v_lshl_add_u64 v[184:185], s[2:3], 0, v[178:179]
	s_add_i32 m0, s24, 0xe000
	s_nop 0
	global_load_lds_dwordx4 v[184:185], off
	s_waitcnt vmcnt(8)
	s_waitcnt lgkmcnt(0)
	s_barrier
	s_waitcnt lgkmcnt(0)
	v_mfma_f32_16x16x32_bf16 v[124:127], v[128:131], v[160:163], v[124:127]
	v_mfma_f32_16x16x32_bf16 v[120:123], v[136:139], v[160:163], v[120:123]
	v_mfma_f32_16x16x32_bf16 v[112:115], v[128:131], v[192:195], v[112:115]
	v_mfma_f32_16x16x32_bf16 v[104:107], v[136:139], v[192:195], v[104:107]
	v_mfma_f32_16x16x32_bf16 v[96:99], v[128:131], v[200:203], v[96:99]
	v_mfma_f32_16x16x32_bf16 v[88:91], v[136:139], v[200:203], v[88:91]
	v_mfma_f32_16x16x32_bf16 v[80:83], v[128:131], v[208:211], v[80:83]
	v_mfma_f32_16x16x32_bf16 v[72:75], v[136:139], v[208:211], v[72:75]
	v_mfma_f32_16x16x32_bf16 v[124:127], v[132:135], v[164:167], v[124:127]
	v_mfma_f32_16x16x32_bf16 v[120:123], v[140:143], v[164:167], v[120:123]
	v_mfma_f32_16x16x32_bf16 v[112:115], v[132:135], v[196:199], v[112:115]
	v_mfma_f32_16x16x32_bf16 v[104:107], v[140:143], v[196:199], v[104:107]
	v_mfma_f32_16x16x32_bf16 v[96:99], v[132:135], v[204:207], v[96:99]
	v_mfma_f32_16x16x32_bf16 v[88:91], v[140:143], v[204:207], v[88:91]
	v_mfma_f32_16x16x32_bf16 v[80:83], v[132:135], v[212:215], v[80:83]
	v_mfma_f32_16x16x32_bf16 v[72:75], v[140:143], v[212:215], v[72:75]
	v_mfma_f32_16x16x32_bf16 v[116:119], v[144:147], v[160:163], v[116:119]
	v_mfma_f32_16x16x32_bf16 v[108:111], v[152:155], v[160:163], v[108:111]
	v_mfma_f32_16x16x32_bf16 v[100:103], v[144:147], v[192:195], v[100:103]
	v_mfma_f32_16x16x32_bf16 v[92:95], v[152:155], v[192:195], v[92:95]
	v_mfma_f32_16x16x32_bf16 v[84:87], v[144:147], v[200:203], v[84:87]
	v_mfma_f32_16x16x32_bf16 v[76:79], v[152:155], v[200:203], v[76:79]
	v_mfma_f32_16x16x32_bf16 v[68:71], v[144:147], v[208:211], v[68:71]
	v_mfma_f32_16x16x32_bf16 v[64:67], v[152:155], v[208:211], v[64:67]
	v_mfma_f32_16x16x32_bf16 v[116:119], v[148:151], v[164:167], v[116:119]
	v_mfma_f32_16x16x32_bf16 v[108:111], v[156:159], v[164:167], v[108:111]
	v_mfma_f32_16x16x32_bf16 v[100:103], v[148:151], v[196:199], v[100:103]
	v_mfma_f32_16x16x32_bf16 v[92:95], v[156:159], v[196:199], v[92:95]
	v_mfma_f32_16x16x32_bf16 v[84:87], v[148:151], v[204:207], v[84:87]
	v_mfma_f32_16x16x32_bf16 v[76:79], v[156:159], v[204:207], v[76:79]
	v_mfma_f32_16x16x32_bf16 v[68:71], v[148:151], v[212:215], v[68:71]
	v_mfma_f32_16x16x32_bf16 v[64:67], v[156:159], v[212:215], v[64:67]
	s_barrier
	s_add_i32 s2, s38, s21
	v_lshl_add_u64 v[184:185], s[16:17], 0, v[170:171]
	s_mov_b32 m0, s2
	ds_read_b128 v[160:163], v191 offset:16384
	ds_read_b128 v[164:167], v191 offset:17408
	ds_read_b128 v[192:195], v191 offset:18432
	ds_read_b128 v[196:199], v191 offset:19456
	ds_read_b128 v[200:203], v191 offset:20480
	ds_read_b128 v[204:207], v191 offset:21504
	ds_read_b128 v[208:211], v191 offset:22528
	ds_read_b128 v[212:215], v191 offset:23552
	global_load_lds_dwordx4 v[184:185], off
	s_add_i32 m0, s2, 0x2000
	s_add_u32 s2, s16, 0xb0000
	v_lshl_add_u64 v[216:217], s[16:17], 0, v[174:175]
	s_addc_u32 s3, s17, 0
	s_add_i32 s59, s39, s21
	global_load_lds_dwordx4 v[216:217], off
	v_lshl_add_u64 v[218:219], s[2:3], 0, v[170:171]
	s_mov_b32 m0, s59
	v_lshl_add_u64 v[220:221], s[18:19], 0, v[172:173]
	global_load_lds_dwordx4 v[218:219], off
	v_lshl_add_u64 v[218:219], s[2:3], 0, v[174:175]
	s_add_i32 m0, s59, 0x2000
	s_nop 0
	global_load_lds_dwordx4 v[218:219], off
	v_lshl_add_u64 v[218:219], s[18:19], 0, v[168:169]
	s_mov_b32 m0, s24
	s_nop 0
	global_load_lds_dwordx4 v[218:219], off
	s_mov_b32 m0, s25
	s_nop 0
	global_load_lds_dwordx4 v[220:221], off
	s_waitcnt vmcnt(8)
	s_waitcnt lgkmcnt(0)
	s_barrier
; #define PG8_STAGE(bufoff, gbase, voff) do { _Pragma("unroll") for (int _i = 0; _i < 2; ++_i) \
;         __builtin_amdgcn_global_load_lds((const unsigned*)((const char*)(gbase) + (voff)[_i]), (PG8_LAS unsigned*)(lds + (bufoff) + ldsw + _i * 8192), 16, 0, 0); } while (0)
; #define PG8_LDA(dst, b, h) do { _Pragma("unroll") for (int m = 0; m < 4; ++m) _Pragma("unroll") for (int k = 0; k < 2; ++k) dst[m][k] = *(const PG8_LAS bf16x8*)(lds + PG8_SA(b, h) + aoff + m * 2048 + k * 1024); } while (0)
; #define PG8_LDB(dst, b, h) do { _Pragma("unroll") for (int n = 0; n < 2; ++n) _Pragma("unroll") for (int k = 0; k < 2; ++k) dst[n][k] = *(const PG8_LAS bf16x8*)(lds + PG8_SB(b, h) + boff + n * 2048 + k * 1024); } while (0)
; #define PG8_MMA(ai, bj, At, Bt) do { __builtin_amdgcn_s_setprio(1); _Pragma("unroll") for (int m = 0; m < 4; ++m) _Pragma("unroll") for (int n = 0; n < 2; ++n) _Pragma("unroll") for (int k = 0; k < 2; ++k) \
;         acc[ai][bj][m][n] = __builtin_amdgcn_mfma_f32_16x16x32_bf16(Bt[n][k], At[m][k], acc[ai][bj][m][n], 0, 0, 0); __builtin_amdgcn_s_setprio(0); } while (0)
; #define PG8_WAIT_V(n) asm volatile("s_waitcnt vmcnt(" #n ")" ::: "memory")
; #define PG8_WAIT_L(n) asm volatile("s_waitcnt lgkmcnt(" #n ")" ::: "memory")
; #define PG8_BAR __builtin_amdgcn_s_barrier()
; #define PG8_SCHED __builtin_amdgcn_sched_barrier(0)
; template <class Epi, class Sched, bool ALIGN_EPI = false, bool SP2 = false>
; __device__ __forceinline__ void gemm_phase(PG8_LAS unsigned char* lds, const Gemm g, const Sched& S, const Epi& E, const int wave_s) {
;     ...
;             PG8_WAIT_V(8); PG8_WAIT_L(0); PG8_BAR; PG8_MMA(1, 0, At, B0); PG8_MMA(1, 1, At, B1); PG8_BAR; PG8_SCHED;
;             PG8_LDB(B0, 1, 0); PG8_LDB(B1, 1, 1); PG8_SCHED; PG8_LDA(At, 1, 0); PG8_STAGE(PG8_SA(0, 1), a2 + hstep, voffA);
;             PG8_WAIT_V(8); PG8_WAIT_L(0); PG8_BAR; PG8_MMA(0, 0, At, B0); PG8_MMA(0, 1, At, B1); PG8_BAR; PG8_SCHED;
	s_waitcnt lgkmcnt(0)
	v_mfma_f32_16x16x32_bf16 v[60:63], v[128:131], v[160:163], v[60:63]
	v_mfma_f32_16x16x32_bf16 v[56:59], v[136:139], v[160:163], v[56:59]
	v_mfma_f32_16x16x32_bf16 v[48:51], v[128:131], v[192:195], v[48:51]
	v_mfma_f32_16x16x32_bf16 v[40:43], v[136:139], v[192:195], v[40:43]
	v_mfma_f32_16x16x32_bf16 v[32:35], v[128:131], v[200:203], v[32:35]
	v_mfma_f32_16x16x32_bf16 v[24:27], v[136:139], v[200:203], v[24:27]
	v_mfma_f32_16x16x32_bf16 v[16:19], v[128:131], v[208:211], v[16:19]
	v_mfma_f32_16x16x32_bf16 v[8:11], v[136:139], v[208:211], v[8:11]
	v_mfma_f32_16x16x32_bf16 v[60:63], v[132:135], v[164:167], v[60:63]
	v_mfma_f32_16x16x32_bf16 v[56:59], v[140:143], v[164:167], v[56:59]
	v_mfma_f32_16x16x32_bf16 v[48:51], v[132:135], v[196:199], v[48:51]
	v_mfma_f32_16x16x32_bf16 v[40:43], v[140:143], v[196:199], v[40:43]
	v_mfma_f32_16x16x32_bf16 v[32:35], v[132:135], v[204:207], v[32:35]
	v_mfma_f32_16x16x32_bf16 v[24:27], v[140:143], v[204:207], v[24:27]
	v_mfma_f32_16x16x32_bf16 v[16:19], v[132:135], v[212:215], v[16:19]
	v_mfma_f32_16x16x32_bf16 v[8:11], v[140:143], v[212:215], v[8:11]
	v_mfma_f32_16x16x32_bf16 v[52:55], v[144:147], v[160:163], v[52:55]
	v_mfma_f32_16x16x32_bf16 v[44:47], v[152:155], v[160:163], v[44:47]
	v_mfma_f32_16x16x32_bf16 v[36:39], v[144:147], v[192:195], v[36:39]
	v_mfma_f32_16x16x32_bf16 v[28:31], v[152:155], v[192:195], v[28:31]
	v_mfma_f32_16x16x32_bf16 v[20:23], v[144:147], v[200:203], v[20:23]
	v_mfma_f32_16x16x32_bf16 v[12:15], v[152:155], v[200:203], v[12:15]
	v_mfma_f32_16x16x32_bf16 v[4:7], v[144:147], v[208:211], v[4:7]
	v_mfma_f32_16x16x32_bf16 v[0:3], v[152:155], v[208:211], v[0:3]
	v_mfma_f32_16x16x32_bf16 v[52:55], v[148:151], v[164:167], v[52:55]
	v_mfma_f32_16x16x32_bf16 v[44:47], v[156:159], v[164:167], v[44:47]
	v_mfma_f32_16x16x32_bf16 v[36:39], v[148:151], v[196:199], v[36:39]
	v_mfma_f32_16x16x32_bf16 v[28:31], v[156:159], v[196:199], v[28:31]
	v_mfma_f32_16x16x32_bf16 v[20:23], v[148:151], v[204:207], v[20:23]
	v_mfma_f32_16x16x32_bf16 v[12:15], v[156:159], v[204:207], v[12:15]
	v_mfma_f32_16x16x32_bf16 v[4:7], v[148:151], v[212:215], v[4:7]
	v_mfma_f32_16x16x32_bf16 v[0:3], v[156:159], v[212:215], v[0:3]
	s_barrier
	s_add_i32 s59, 0, 0x18000
	s_add_i32 s60, 0, 0x1c000
	v_add_u32_e32 v140, s59, v188
	v_add_u32_e32 v156, s60, v188
	ds_read_b128 v[128:131], v140
	ds_read_b128 v[132:135], v140 offset:1024
	ds_read_b128 v[136:139], v140 offset:2048
	ds_read_b128 v[140:143], v140 offset:3072
	ds_read_b128 v[144:147], v156
	ds_read_b128 v[148:151], v156 offset:1024
	ds_read_b128 v[152:155], v156 offset:2048
	ds_read_b128 v[156:159], v156 offset:3072
	s_add_u32 s2, s18, 0xb0000
	s_addc_u32 s3, s19, 0
	s_mov_b32 m0, s26
	v_lshl_add_u64 v[222:223], s[2:3], 0, v[168:169]
	ds_read_b128 v[160:163], v191 offset:32768
	ds_read_b128 v[164:167], v191 offset:33792
	ds_read_b128 v[192:195], v191 offset:34816
	ds_read_b128 v[196:199], v191 offset:35840
	ds_read_b128 v[200:203], v191 offset:36864
	ds_read_b128 v[204:207], v191 offset:37888
	ds_read_b128 v[208:211], v191 offset:38912
	ds_read_b128 v[212:215], v191 offset:39936
	global_load_lds_dwordx4 v[222:223], off
	v_lshl_add_u64 v[222:223], s[2:3], 0, v[172:173]
	s_mov_b32 m0, s27
	s_nop 0
	global_load_lds_dwordx4 v[222:223], off
	s_waitcnt vmcnt(8)
	s_waitcnt lgkmcnt(0)
	s_barrier
	s_waitcnt lgkmcnt(0)
	v_mfma_f32_16x16x32_bf16 v[124:127], v[128:131], v[160:163], v[124:127]
	v_mfma_f32_16x16x32_bf16 v[120:123], v[136:139], v[160:163], v[120:123]
	v_mfma_f32_16x16x32_bf16 v[112:115], v[128:131], v[192:195], v[112:115]
	v_mfma_f32_16x16x32_bf16 v[104:107], v[136:139], v[192:195], v[104:107]
	v_mfma_f32_16x16x32_bf16 v[96:99], v[128:131], v[200:203], v[96:99]
	v_mfma_f32_16x16x32_bf16 v[88:91], v[136:139], v[200:203], v[88:91]
	v_mfma_f32_16x16x32_bf16 v[80:83], v[128:131], v[208:211], v[80:83]
	v_mfma_f32_16x16x32_bf16 v[72:75], v[136:139], v[208:211], v[72:75]
	v_mfma_f32_16x16x32_bf16 v[124:127], v[132:135], v[164:167], v[124:127]
	v_mfma_f32_16x16x32_bf16 v[120:123], v[140:143], v[164:167], v[120:123]
	v_mfma_f32_16x16x32_bf16 v[112:115], v[132:135], v[196:199], v[112:115]
	v_mfma_f32_16x16x32_bf16 v[104:107], v[140:143], v[196:199], v[104:107]
	v_mfma_f32_16x16x32_bf16 v[96:99], v[132:135], v[204:207], v[96:99]
	v_mfma_f32_16x16x32_bf16 v[88:91], v[140:143], v[204:207], v[88:91]
	v_mfma_f32_16x16x32_bf16 v[80:83], v[132:135], v[212:215], v[80:83]
	v_mfma_f32_16x16x32_bf16 v[72:75], v[140:143], v[212:215], v[72:75]
	v_mfma_f32_16x16x32_bf16 v[116:119], v[144:147], v[160:163], v[116:119]
	v_mfma_f32_16x16x32_bf16 v[108:111], v[152:155], v[160:163], v[108:111]
	v_mfma_f32_16x16x32_bf16 v[100:103], v[144:147], v[192:195], v[100:103]
	v_mfma_f32_16x16x32_bf16 v[92:95], v[152:155], v[192:195], v[92:95]
	v_mfma_f32_16x16x32_bf16 v[84:87], v[144:147], v[200:203], v[84:87]
	v_mfma_f32_16x16x32_bf16 v[76:79], v[152:155], v[200:203], v[76:79]
	v_mfma_f32_16x16x32_bf16 v[68:71], v[144:147], v[208:211], v[68:71]
	v_mfma_f32_16x16x32_bf16 v[64:67], v[152:155], v[208:211], v[64:67]
	v_mfma_f32_16x16x32_bf16 v[116:119], v[148:151], v[164:167], v[116:119]
	v_mfma_f32_16x16x32_bf16 v[108:111], v[156:159], v[164:167], v[108:111]
	v_mfma_f32_16x16x32_bf16 v[100:103], v[148:151], v[196:199], v[100:103]
	v_mfma_f32_16x16x32_bf16 v[92:95], v[156:159], v[196:199], v[92:95]
	v_mfma_f32_16x16x32_bf16 v[84:87], v[148:151], v[204:207], v[84:87]
	v_mfma_f32_16x16x32_bf16 v[76:79], v[156:159], v[204:207], v[76:79]
	v_mfma_f32_16x16x32_bf16 v[68:71], v[148:151], v[212:215], v[68:71]
	v_mfma_f32_16x16x32_bf16 v[64:67], v[156:159], v[212:215], v[64:67]
	s_barrier
; #define PG8_STAGE(bufoff, gbase, voff) do { _Pragma("unroll") for (int _i = 0; _i < 2; ++_i) \
;         __builtin_amdgcn_global_load_lds((const unsigned*)((const char*)(gbase) + (voff)[_i]), (PG8_LAS unsigned*)(lds + (bufoff) + ldsw + _i * 8192), 16, 0, 0); } while (0)
; #define PG8_LDA(dst, b, h) do { _Pragma("unroll") for (int m = 0; m < 4; ++m) _Pragma("unroll") for (int k = 0; k < 2; ++k) dst[m][k] = *(const PG8_LAS bf16x8*)(lds + PG8_SA(b, h) + aoff + m * 2048 + k * 1024); } while (0)
; #define PG8_MMA(ai, bj, At, Bt) do { __builtin_amdgcn_s_setprio(1); _Pragma("unroll") for (int m = 0; m < 4; ++m) _Pragma("unroll") for (int n = 0; n < 2; ++n) _Pragma("unroll") for (int k = 0; k < 2; ++k) \
;         acc[ai][bj][m][n] = __builtin_amdgcn_mfma_f32_16x16x32_bf16(Bt[n][k], At[m][k], acc[ai][bj][m][n], 0, 0, 0); __builtin_amdgcn_s_setprio(0); } while (0)
; #define PG8_WAIT_V(n) asm volatile("s_waitcnt vmcnt(" #n ")" ::: "memory")
; #define PG8_WAIT_L(n) asm volatile("s_waitcnt lgkmcnt(" #n ")" ::: "memory")
; #define PG8_BAR __builtin_amdgcn_s_barrier()
; #define PG8_SCHED __builtin_amdgcn_sched_barrier(0)
; template <class Epi, class Sched, bool ALIGN_EPI = false, bool SP2 = false>
; __device__ __forceinline__ void gemm_phase(PG8_LAS unsigned char* lds, const Gemm g, const Sched& S, const Epi& E, const int wave_s) {
;     ...
;             PG8_LDA(At, 1, 1); PG8_STAGE(PG8_SB(1, 0), b3, voffB); PG8_STAGE(PG8_SB(1, 1), b3 + hstep, voffB); PG8_STAGE(PG8_SA(1, 0), a3, voffA);
;             PG8_WAIT_V(8); PG8_WAIT_L(0); PG8_BAR; PG8_MMA(1, 0, At, B0); PG8_MMA(1, 1, At, B1); PG8_BAR; PG8_SCHED;
	s_add_i32 s2, s59, s21
	v_lshl_add_u64 v[184:185], v[184:185], 0, s[8:9]
	s_mov_b32 m0, s2
	ds_read_b128 v[160:163], v191 offset:49152
	ds_read_b128 v[164:167], v191 offset:50176
	ds_read_b128 v[192:195], v191 offset:51200
	ds_read_b128 v[196:199], v191 offset:52224
	ds_read_b128 v[200:203], v191 offset:53248
	ds_read_b128 v[204:207], v191 offset:54272
	ds_read_b128 v[208:211], v191 offset:55296
	ds_read_b128 v[212:215], v191 offset:56320
	global_load_lds_dwordx4 v[184:185], off
	s_add_i32 m0, s2, 0x2000
	s_add_u32 s2, s16, 0xb0080
	v_lshl_add_u64 v[184:185], v[216:217], 0, s[8:9]
	s_addc_u32 s3, s17, 0
	s_add_i32 s16, s60, s21
	global_load_lds_dwordx4 v[184:185], off
	v_lshl_add_u64 v[184:185], s[2:3], 0, v[170:171]
	s_mov_b32 m0, s16
	s_nop 0
	global_load_lds_dwordx4 v[184:185], off
	v_lshl_add_u64 v[184:185], s[2:3], 0, v[174:175]
	s_add_i32 m0, s16, 0x2000
	s_nop 0
	global_load_lds_dwordx4 v[184:185], off
	v_lshl_add_u64 v[184:185], v[218:219], 0, s[8:9]
	s_mov_b32 m0, s33
	s_nop 0
	global_load_lds_dwordx4 v[184:185], off
	v_lshl_add_u64 v[184:185], v[220:221], 0, s[8:9]
	s_mov_b32 m0, s34
	s_nop 0
	global_load_lds_dwordx4 v[184:185], off
	s_waitcnt vmcnt(8)
	s_waitcnt lgkmcnt(0)
	s_barrier
	s_waitcnt lgkmcnt(0)
	v_mfma_f32_16x16x32_bf16 v[60:63], v[128:131], v[160:163], v[60:63]
	v_mfma_f32_16x16x32_bf16 v[56:59], v[136:139], v[160:163], v[56:59]
	v_mfma_f32_16x16x32_bf16 v[48:51], v[128:131], v[192:195], v[48:51]
	v_mfma_f32_16x16x32_bf16 v[40:43], v[136:139], v[192:195], v[40:43]
	v_mfma_f32_16x16x32_bf16 v[32:35], v[128:131], v[200:203], v[32:35]
	v_mfma_f32_16x16x32_bf16 v[24:27], v[136:139], v[200:203], v[24:27]
	v_mfma_f32_16x16x32_bf16 v[16:19], v[128:131], v[208:211], v[16:19]
	v_mfma_f32_16x16x32_bf16 v[8:11], v[136:139], v[208:211], v[8:11]
	v_mfma_f32_16x16x32_bf16 v[60:63], v[132:135], v[164:167], v[60:63]
	v_mfma_f32_16x16x32_bf16 v[56:59], v[140:143], v[164:167], v[56:59]
	v_mfma_f32_16x16x32_bf16 v[48:51], v[132:135], v[196:199], v[48:51]
	v_mfma_f32_16x16x32_bf16 v[40:43], v[140:143], v[196:199], v[40:43]
	v_mfma_f32_16x16x32_bf16 v[32:35], v[132:135], v[204:207], v[32:35]
	v_mfma_f32_16x16x32_bf16 v[24:27], v[140:143], v[204:207], v[24:27]
	v_mfma_f32_16x16x32_bf16 v[16:19], v[132:135], v[212:215], v[16:19]
	v_mfma_f32_16x16x32_bf16 v[8:11], v[140:143], v[212:215], v[8:11]
	v_mfma_f32_16x16x32_bf16 v[52:55], v[144:147], v[160:163], v[52:55]
	v_mfma_f32_16x16x32_bf16 v[44:47], v[152:155], v[160:163], v[44:47]
	v_mfma_f32_16x16x32_bf16 v[36:39], v[144:147], v[192:195], v[36:39]
	v_mfma_f32_16x16x32_bf16 v[28:31], v[152:155], v[192:195], v[28:31]
	v_mfma_f32_16x16x32_bf16 v[20:23], v[144:147], v[200:203], v[20:23]
	v_mfma_f32_16x16x32_bf16 v[12:15], v[152:155], v[200:203], v[12:15]
	v_mfma_f32_16x16x32_bf16 v[4:7], v[144:147], v[208:211], v[4:7]
	v_mfma_f32_16x16x32_bf16 v[0:3], v[152:155], v[208:211], v[0:3]
	v_mfma_f32_16x16x32_bf16 v[52:55], v[148:151], v[164:167], v[52:55]
	v_mfma_f32_16x16x32_bf16 v[44:47], v[156:159], v[164:167], v[44:47]
	v_mfma_f32_16x16x32_bf16 v[36:39], v[148:151], v[196:199], v[36:39]
	v_mfma_f32_16x16x32_bf16 v[28:31], v[156:159], v[196:199], v[28:31]
	v_mfma_f32_16x16x32_bf16 v[20:23], v[148:151], v[204:207], v[20:23]
	v_mfma_f32_16x16x32_bf16 v[12:15], v[156:159], v[204:207], v[12:15]
	v_mfma_f32_16x16x32_bf16 v[4:7], v[148:151], v[212:215], v[4:7]
	v_mfma_f32_16x16x32_bf16 v[0:3], v[156:159], v[212:215], v[0:3]
	s_barrier
	s_add_i32 s58, s58, 2
	s_add_u32 s54, s54, 0x100
	s_addc_u32 s55, s55, 0
	s_cmp_gt_u32 s58, 41
	s_mov_b64 s[2:3], s[14:15]
	s_cbranch_scc0 .LBB0_838
	s_and_b64 vcc, exec, s[10:11]
	s_cbranch_vccz .LBB0_841
	s_barrier
